# P10 final-norm loop software-pipelined (next row loads issued before current stores); P6 epilogue rewritten with 6-step-ahead residual prefetch and 128B-wide loads/stores
# speedup vs baseline: 1.0173x; 1.0066x over previous
; #define G8_STAGE(bufoff, gbase, NM) do { _Pragma("unroll") for (int _i = 0; _i < 2; ++_i) { \
;     const char* _b = (const char*)(gbase) + (_i ? p2##NM : (size_t)0); asm volatile("" : "+s"(_b));     \
;     __builtin_amdgcn_global_load_lds((const unsigned*)(_b + voff##NM), (LAS unsigned*)(lds + (bufoff) + ldsw + _i * 8192), 16, 0, 0); } } while (0)
; #define G8_WAIT_V(n) asm volatile("s_waitcnt vmcnt(" #n ")" ::: "memory")
; #define G8_BAR __builtin_amdgcn_s_barrier()
;     ...
;   const unsigned ldsw = (unsigned)wid * 1024u;
;   const int aoff = lds_byte(wr * 64 + fr, fq * 8), boff = lds_byte(wc * 32 + fr, fq * 8);
;     ...
;   G8_STAGE(G8_SB(0, 0), cB, B); G8_STAGE(G8_SB(0, 1), cB + hstepB, B); G8_STAGE(G8_SA(0, 0), cA, A); G8_STAGE(G8_SA(0, 1), cA + hstepA, A);
;   if (wr == 1) G8_BAR;
;   G8_WAIT_V(2); G8_BAR;
;   G8_STAGE(G8_SB(1, 0), cB + kstep, B); G8_STAGE(G8_SA(1, 0), cA + kstep, A); G8_STAGE(G8_SB(1, 1), cB + hstepB + kstep, B);
;   G8_WAIT_V(6); G8_BAR;
.LBB0_1068:
	s_lshl_b32 s11, s11, 13
	s_lshl_b32 s12, s12, 13
	s_and_b32 s11, s11, 0x6000
	s_add_u32 s14, s26, 0x80
	s_addc_u32 s15, s27, 0
	s_waitcnt vmcnt(2)
	s_barrier
	s_add_i32 m0, s3, 0x18000
	v_and_b32_e32 v1, 15, v0
	v_lshl_add_u64 v[2:3], s[14:15], 0, v[130:131]
	s_add_u32 s14, s26, 0x40080
	s_addc_u32 s15, s27, 0
	global_load_lds_dwordx4 v[2:3], off
	s_add_i32 m0, s3, 0x1a000
	v_lshl_add_u64 v[2:3], s[14:15], 0, v[130:131]
	s_add_u32 s14, s24, 0x80
	s_addc_u32 s15, s25, 0
	global_load_lds_dwordx4 v[2:3], off
	s_add_i32 s40, s3, 0x8000
	v_lshl_add_u64 v[2:3], s[14:15], 0, v[128:129]
	s_add_u32 s14, s24, 0x40080
	s_mov_b32 m0, s40
	s_addc_u32 s15, s25, 0
	global_load_lds_dwordx4 v[2:3], off
	s_add_i32 s41, s3, 0xa000
	v_lshl_add_u64 v[2:3], s[14:15], 0, v[128:129]
	s_add_u32 s14, s26, 0x80080
	s_mov_b32 m0, s41
	s_addc_u32 s15, s27, 0
	global_load_lds_dwordx4 v[2:3], off
	s_add_i32 m0, s3, 0x1c000
	v_lshlrev_b32_e32 v1, 6, v1
	v_lshl_add_u64 v[2:3], s[14:15], 0, v[130:131]
	s_add_u32 s14, s26, 0xc0080
	s_addc_u32 s15, s27, 0
	global_load_lds_dwordx4 v[2:3], off
	s_add_i32 m0, s3, 0x1e000
	v_lshl_add_u64 v[2:3], s[14:15], 0, v[130:131]
	global_load_lds_dwordx4 v[2:3], off
	v_and_b32_e32 v2, 48, v0
	v_lshlrev_b32_e32 v0, 2, v0
	v_and_b32_e32 v0, 32, v0
	v_or_b32_e32 v3, v1, v2
	v_bitop3_b32 v1, v1, v0, v2 bitop3:0x36
	s_waitcnt vmcnt(6)
	s_cmpk_lt_u32 s10, 0x100
	v_bitop3_b32 v0, v3, s12, v0 bitop3:0xde
	v_or_b32_e32 v136, s11, v1
	s_cselect_b64 s[10:11], -1, 0
	s_add_i32 s42, 0, 0x10000
	s_add_i32 s43, 0, 0x14000
	v_add_u32_e32 v137, s42, v136
	v_add_u32_e32 v138, 0x1000, v137
	v_add_u32_e32 v139, 0, v0
	s_mov_b32 s12, 0x3a800000
	s_movk_i32 s44, 0x1080
	s_mov_b64 s[18:19], s[24:25]
	s_mov_b64 s[20:21], s[26:27]
	s_barrier
	s_branch .LBB0_1071

; #define G8_STAGE(bufoff, gbase, NM) do { _Pragma("unroll") for (int _i = 0; _i < 2; ++_i) { \
;     const char* _b = (const char*)(gbase) + (_i ? p2##NM : (size_t)0); asm volatile("" : "+s"(_b));     \
;     __builtin_amdgcn_global_load_lds((const unsigned*)(_b + voff##NM), (LAS unsigned*)(lds + (bufoff) + ldsw + _i * 8192), 16, 0, 0); } } while (0)
; #define G8_WAIT_V(n) asm volatile("s_waitcnt vmcnt(" #n ")" ::: "memory")
; #define G8_WAIT_L(n) asm volatile("s_waitcnt lgkmcnt(" #n ")" ::: "memory")
; #define G8_BAR __builtin_amdgcn_s_barrier()
; #define G8_SCHED __builtin_amdgcn_sched_barrier(0)
;     ...
;       G8_LDB(B0, 0, 0); G8_LDB(B1, 0, 1); G8_SCHED; G8_LDA(At, 0, 0); G8_STAGE(G8_SA(1, 1), a1, A);
;       const bool d0a = (BD == 0) || (BD == 1 && t < (nt >> 1)) || (BD == 2 && !(cur.pn & 1));
;       const bool d1a = (BD == 0) || (BD == 1 && t >= (nt >> 1)) || (BD == 2 && !(cur.pn & 1));
;       const bool d0b = (BD == 0) || (BD == 1 && t < (nt >> 1)) || (BD == 2 && (cur.pn & 1));
;       const bool d1b = (BD == 0) || (BD == 1 && t >= (nt >> 1)) || (BD == 2 && (cur.pn & 1));
;       G8_WAIT_V(8); G8_WAIT_L(0); G8_BAR; if (d0a) G8_MMA(0, 0, At, B0); if (d1a) G8_MMA(0, 1, At, B1); G8_BAR; G8_SCHED;
;       G8_LDA(At, 0, 1); G8_STAGE(G8_SB(0, 0), b2, B); G8_STAGE(G8_SB(0, 1), b2 + hstepB, B); G8_STAGE(G8_SA(0, 0), a2, A);
;       G8_WAIT_V(8); G8_WAIT_L(0); G8_BAR; if (d0a) G8_MMA(1, 0, At, B0); if (d1a) G8_MMA(1, 1, At, B1); G8_BAR; G8_SCHED;
.LBB0_1078:
	s_add_u32 s36, s24, 0x80080
	s_addc_u32 s37, s25, 0
	s_add_u32 s24, s24, 0x100
	s_addc_u32 s25, s25, 0
	s_cmp_eq_u32 s47, 28
	s_cselect_b32 s30, s18, s24
	s_cselect_b32 s31, s19, s25
	s_cselect_b32 s35, s21, s23
	s_cselect_b32 s34, s20, s17
	s_add_u32 s26, s30, 0x80
	s_addc_u32 s27, s31, 0
	s_add_u32 s28, s34, 0x80
	s_addc_u32 s29, s35, 0
	ds_read_b128 v[140:143], v137
	ds_read_b128 v[144:147], v137 offset:1024
	ds_read_b128 v[148:151], v137 offset:2048
	ds_read_b128 v[152:155], v137 offset:3072
	ds_read_b128 v[156:159], v138
	ds_read_b128 v[160:163], v138 offset:1024
	ds_read_b128 v[164:167], v138 offset:2048
	ds_read_b128 v[168:171], v138 offset:3072
	s_add_i32 m0, s3, 0xc000
	s_mov_b64 s[48:49], s[36:37]
	s_add_u32 s36, s36, 0x40000
	ds_read_b128 v[172:175], v139
	ds_read_b128 v[176:179], v139 offset:1024
	ds_read_b128 v[180:183], v139 offset:2048
	ds_read_b128 v[184:187], v139 offset:3072
	ds_read_b128 v[188:191], v139 offset:4096
	ds_read_b128 v[192:195], v139 offset:5120
	ds_read_b128 v[202:205], v139 offset:6144
	ds_read_b128 v[206:209], v139 offset:7168
	s_addc_u32 s37, s37, 0
	v_lshl_add_u64 v[132:133], s[48:49], 0, v[128:129]
	global_load_lds_dwordx4 v[132:133], off
	s_add_i32 m0, s3, 0xe000
	v_lshl_add_u64 v[132:133], s[36:37], 0, v[128:129]
	global_load_lds_dwordx4 v[132:133], off
	s_waitcnt vmcnt(8)
	s_waitcnt lgkmcnt(0)
	s_barrier
	s_setprio 1
	s_waitcnt lgkmcnt(0)
	v_mfma_f32_16x16x128_f8f6f4 v[124:127], v[140:147], v[172:179], v[124:127]
	v_mfma_f32_16x16x128_f8f6f4 v[120:123], v[148:155], v[172:179], v[120:123]
	v_mfma_f32_16x16x128_f8f6f4 v[108:111], v[140:147], v[180:187], v[108:111]
	v_mfma_f32_16x16x128_f8f6f4 v[104:107], v[148:155], v[180:187], v[104:107]
	v_mfma_f32_16x16x128_f8f6f4 v[132:135], v[140:147], v[188:195], v[92:95]
	v_mfma_f32_16x16x128_f8f6f4 v[196:199], v[148:155], v[188:195], v[88:91]
	v_mfma_f32_16x16x128_f8f6f4 v[210:213], v[140:147], v[202:209], v[76:79]
	v_mfma_f32_16x16x128_f8f6f4 v[214:217], v[148:155], v[202:209], v[72:75]
	s_setprio 0
	s_setprio 1
	v_mfma_f32_16x16x128_f8f6f4 v[116:119], v[156:163], v[172:179], v[116:119]
	v_mfma_f32_16x16x128_f8f6f4 v[112:115], v[164:171], v[172:179], v[112:115]
	v_mfma_f32_16x16x128_f8f6f4 v[100:103], v[156:163], v[180:187], v[100:103]
	v_mfma_f32_16x16x128_f8f6f4 v[96:99], v[164:171], v[180:187], v[96:99]
	v_mfma_f32_16x16x128_f8f6f4 v[172:175], v[156:163], v[188:195], v[84:87]
	v_mfma_f32_16x16x128_f8f6f4 v[176:179], v[164:171], v[188:195], v[80:83]
	v_mfma_f32_16x16x128_f8f6f4 v[180:183], v[156:163], v[202:209], v[68:71]
	v_mfma_f32_16x16x128_f8f6f4 v[184:187], v[164:171], v[202:209], v[64:67]
	s_setprio 0
	s_barrier
	s_mov_b64 s[36:37], s[34:35]
	s_nop 3
	ds_read_b128 v[64:67], v139 offset:16384
	ds_read_b128 v[68:71], v139 offset:17408
	ds_read_b128 v[72:75], v139 offset:18432
	ds_read_b128 v[76:79], v139 offset:19456
	ds_read_b128 v[80:83], v139 offset:20480
	ds_read_b128 v[84:87], v139 offset:21504
	ds_read_b128 v[88:91], v139 offset:22528
	ds_read_b128 v[92:95], v139 offset:23552
	s_add_i32 s48, s42, s2
	v_lshl_add_u64 v[188:189], s[36:37], 0, v[130:131]
	s_add_u32 s36, s34, 0x40000
	s_mov_b32 m0, s48
	s_addc_u32 s37, s35, 0
	global_load_lds_dwordx4 v[188:189], off
	s_add_i32 m0, s48, 0x2000
	v_lshl_add_u64 v[188:189], s[36:37], 0, v[130:131]
	s_add_u32 s36, s34, 0x80000
	s_addc_u32 s37, s35, 0
	global_load_lds_dwordx4 v[188:189], off
	s_nop 0
	v_lshl_add_u64 v[188:189], s[36:37], 0, v[130:131]
	s_add_i32 s36, s43, s2
	s_add_u32 s34, s34, 0xc0000
	s_mov_b32 m0, s36
	s_addc_u32 s35, s35, 0
	global_load_lds_dwordx4 v[188:189], off
	s_add_i32 m0, s36, 0x2000
	v_lshl_add_u64 v[188:189], s[34:35], 0, v[130:131]
	s_mov_b64 s[34:35], s[30:31]
	global_load_lds_dwordx4 v[188:189], off
	s_mov_b32 m0, s3
	v_lshl_add_u64 v[188:189], s[34:35], 0, v[128:129]
	s_add_u32 s34, s30, 0x40000
	s_addc_u32 s35, s31, 0
	global_load_lds_dwordx4 v[188:189], off
	s_mov_b32 m0, s13
	v_lshl_add_u64 v[188:189], s[34:35], 0, v[128:129]
	global_load_lds_dwordx4 v[188:189], off
	s_waitcnt vmcnt(8)
	s_waitcnt lgkmcnt(0)
	s_barrier
	s_setprio 1
	s_waitcnt lgkmcnt(0)
	v_mfma_f32_16x16x128_f8f6f4 v[60:63], v[140:147], v[64:71], v[60:63]
	v_mfma_f32_16x16x128_f8f6f4 v[56:59], v[148:155], v[64:71], v[56:59]
	v_mfma_f32_16x16x128_f8f6f4 v[188:191], v[140:147], v[72:79], v[44:47]
	v_mfma_f32_16x16x128_f8f6f4 v[192:195], v[148:155], v[72:79], v[40:43]
	v_mfma_f32_16x16x128_f8f6f4 v[202:205], v[140:147], v[80:87], v[28:31]
	v_mfma_f32_16x16x128_f8f6f4 v[206:209], v[148:155], v[80:87], v[24:27]
	v_mfma_f32_16x16x128_f8f6f4 v[218:221], v[140:147], v[88:95], v[12:15]
	v_mfma_f32_16x16x128_f8f6f4 v[222:225], v[148:155], v[88:95], v[8:11]
	s_setprio 0
	s_setprio 1
	v_mfma_f32_16x16x128_f8f6f4 v[52:55], v[156:163], v[64:71], v[52:55]
	v_mfma_f32_16x16x128_f8f6f4 v[48:51], v[164:171], v[64:71], v[48:51]
	v_mfma_f32_16x16x128_f8f6f4 v[226:229], v[156:163], v[72:79], v[36:39]
	v_mfma_f32_16x16x128_f8f6f4 v[230:233], v[164:171], v[72:79], v[32:35]
	v_mfma_f32_16x16x128_f8f6f4 v[234:237], v[156:163], v[80:87], v[20:23]
	v_mfma_f32_16x16x128_f8f6f4 v[238:241], v[164:171], v[80:87], v[16:19]
	v_mfma_f32_16x16x128_f8f6f4 v[242:245], v[156:163], v[88:95], v[4:7]
	v_mfma_f32_16x16x128_f8f6f4 v[246:249], v[164:171], v[88:95], v[0:3]
	s_setprio 0
	s_barrier
; #define G8_STAGE(bufoff, gbase, NM) do { _Pragma("unroll") for (int _i = 0; _i < 2; ++_i) { \
;     const char* _b = (const char*)(gbase) + (_i ? p2##NM : (size_t)0); asm volatile("" : "+s"(_b));     \
;     __builtin_amdgcn_global_load_lds((const unsigned*)(_b + voff##NM), (LAS unsigned*)(lds + (bufoff) + ldsw + _i * 8192), 16, 0, 0); } } while (0)
; #define G8_WAIT_V(n) asm volatile("s_waitcnt vmcnt(" #n ")" ::: "memory")
; #define G8_WAIT_L(n) asm volatile("s_waitcnt lgkmcnt(" #n ")" ::: "memory")
; #define G8_BAR __builtin_amdgcn_s_barrier()
; #define G8_SCHED __builtin_amdgcn_sched_barrier(0)
;     ...
;       G8_LDA(At, 0, 1); G8_STAGE(G8_SB(0, 0), b2, B); G8_STAGE(G8_SB(0, 1), b2 + hstepB, B); G8_STAGE(G8_SA(0, 0), a2, A);
;       G8_WAIT_V(8); G8_WAIT_L(0); G8_BAR; if (d0a) G8_MMA(1, 0, At, B0); if (d1a) G8_MMA(1, 1, At, B1); G8_BAR; G8_SCHED;
;       G8_LDB(B0, 1, 0); G8_LDB(B1, 1, 1); G8_SCHED; G8_LDA(At, 1, 0); G8_STAGE(G8_SA(0, 1), a2 + hstepA, A);
;       G8_WAIT_V(8); G8_WAIT_L(0); G8_BAR; if (d0b) G8_MMA(0, 0, At, B0); if (d1b) G8_MMA(0, 1, At, B1); G8_BAR; G8_SCHED;
;       G8_LDA(At, 1, 1); G8_STAGE(G8_SB(1, 0), b3, B); G8_STAGE(G8_SB(1, 1), b3 + hstepB, B); G8_STAGE(G8_SA(1, 0), a3, A);
;       G8_WAIT_V(8); G8_WAIT_L(0); G8_BAR; if (d0b) G8_MMA(1, 0, At, B0); if (d1b) G8_MMA(1, 1, At, B1); G8_BAR; G8_SCHED;
;     }
	s_add_i32 s36, 0, 0x18000
	v_add_u32_e32 v8, s36, v136
	s_add_i32 s37, 0, 0x1c000
	s_nop 1
	ds_read_b128 v[0:3], v8
	ds_read_b128 v[4:7], v8 offset:1024
	ds_read_b128 v[16:19], v8 offset:2048
	ds_read_b128 v[20:23], v8 offset:3072
	v_add_u32_e32 v8, 0x1000, v8
	ds_read_b128 v[140:143], v8
	ds_read_b128 v[144:147], v8 offset:1024
	ds_read_b128 v[148:151], v8 offset:2048
	ds_read_b128 v[152:155], v8 offset:3072
	s_add_u32 s34, s30, 0x80000
	s_addc_u32 s35, s31, 0
	s_add_u32 s30, s30, 0xc0000
	s_mov_b32 m0, s33
	ds_read_b128 v[8:11], v139 offset:32768
	ds_read_b128 v[12:15], v139 offset:33792
	ds_read_b128 v[24:27], v139 offset:34816
	ds_read_b128 v[28:31], v139 offset:35840
	ds_read_b128 v[32:35], v139 offset:36864
	ds_read_b128 v[36:39], v139 offset:37888
	ds_read_b128 v[40:43], v139 offset:38912
	ds_read_b128 v[44:47], v139 offset:39936
	s_addc_u32 s31, s31, 0
	v_lshl_add_u64 v[64:65], s[34:35], 0, v[128:129]
	global_load_lds_dwordx4 v[64:65], off
	s_mov_b32 m0, s38
	v_lshl_add_u64 v[64:65], s[30:31], 0, v[128:129]
	global_load_lds_dwordx4 v[64:65], off
	s_waitcnt vmcnt(8)
	s_waitcnt lgkmcnt(0)
	s_barrier
	s_setprio 1
	s_waitcnt lgkmcnt(0)
	v_mfma_f32_16x16x128_f8f6f4 v[124:127], v[0:7], v[8:15], v[124:127]
	v_mfma_f32_16x16x128_f8f6f4 v[120:123], v[16:23], v[8:15], v[120:123]
	v_mfma_f32_16x16x128_f8f6f4 v[108:111], v[0:7], v[24:31], v[108:111]
	v_mfma_f32_16x16x128_f8f6f4 v[104:107], v[16:23], v[24:31], v[104:107]
	v_mfma_f32_16x16x128_f8f6f4 v[92:95], v[0:7], v[32:39], v[132:135]
	v_mfma_f32_16x16x128_f8f6f4 v[88:91], v[16:23], v[32:39], v[196:199]
	v_mfma_f32_16x16x128_f8f6f4 v[76:79], v[0:7], v[40:47], v[210:213]
	v_mfma_f32_16x16x128_f8f6f4 v[72:75], v[16:23], v[40:47], v[214:217]
	s_setprio 0
	s_setprio 1
	v_mfma_f32_16x16x128_f8f6f4 v[116:119], v[140:147], v[8:15], v[116:119]
	v_mfma_f32_16x16x128_f8f6f4 v[112:115], v[148:155], v[8:15], v[112:115]
	v_mfma_f32_16x16x128_f8f6f4 v[100:103], v[140:147], v[24:31], v[100:103]
	v_mfma_f32_16x16x128_f8f6f4 v[96:99], v[148:155], v[24:31], v[96:99]
	v_mfma_f32_16x16x128_f8f6f4 v[84:87], v[140:147], v[32:39], v[172:175]
	v_mfma_f32_16x16x128_f8f6f4 v[80:83], v[148:155], v[32:39], v[176:179]
	v_mfma_f32_16x16x128_f8f6f4 v[68:71], v[140:147], v[40:47], v[180:183]
	v_mfma_f32_16x16x128_f8f6f4 v[64:67], v[148:155], v[40:47], v[184:187]
	s_setprio 0
	s_barrier
	s_mov_b64 s[30:31], s[28:29]
	ds_read_b128 v[32:35], v139 offset:49152
	ds_read_b128 v[36:39], v139 offset:50176
	ds_read_b128 v[156:159], v139 offset:51200
	ds_read_b128 v[160:163], v139 offset:52224
	ds_read_b128 v[164:167], v139 offset:53248
	ds_read_b128 v[168:171], v139 offset:54272
	ds_read_b128 v[172:175], v139 offset:55296
	ds_read_b128 v[176:179], v139 offset:56320
	s_add_i32 s34, s36, s2
	v_lshl_add_u64 v[8:9], s[30:31], 0, v[130:131]
	s_add_u32 s30, s28, 0x40000
	s_mov_b32 m0, s34
	s_addc_u32 s31, s29, 0
	global_load_lds_dwordx4 v[8:9], off
	s_add_i32 m0, s34, 0x2000
	v_lshl_add_u64 v[8:9], s[30:31], 0, v[130:131]
	s_add_u32 s30, s28, 0x80000
	s_addc_u32 s31, s29, 0
	global_load_lds_dwordx4 v[8:9], off
	s_nop 0
	v_lshl_add_u64 v[8:9], s[30:31], 0, v[130:131]
	s_add_i32 s30, s37, s2
	s_add_u32 s28, s28, 0xc0000
	s_mov_b32 m0, s30
	s_addc_u32 s29, s29, 0
	global_load_lds_dwordx4 v[8:9], off
	s_add_i32 m0, s30, 0x2000
	v_lshl_add_u64 v[8:9], s[28:29], 0, v[130:131]
	s_mov_b64 s[28:29], s[26:27]
	s_add_u32 s26, s26, 0x40000
	global_load_lds_dwordx4 v[8:9], off
	s_mov_b32 m0, s40
	v_lshl_add_u64 v[8:9], s[28:29], 0, v[128:129]
	s_addc_u32 s27, s27, 0
	global_load_lds_dwordx4 v[8:9], off
	s_mov_b32 m0, s41
	v_lshl_add_u64 v[8:9], s[26:27], 0, v[128:129]
	global_load_lds_dwordx4 v[8:9], off
	s_waitcnt vmcnt(8)
	s_waitcnt lgkmcnt(0)
	s_barrier
	s_setprio 1
	s_waitcnt lgkmcnt(0)
	v_mfma_f32_16x16x128_f8f6f4 v[60:63], v[0:7], v[32:39], v[60:63]
	v_mfma_f32_16x16x128_f8f6f4 v[56:59], v[16:23], v[32:39], v[56:59]
	v_mfma_f32_16x16x128_f8f6f4 v[44:47], v[0:7], v[156:163], v[188:191]
	v_mfma_f32_16x16x128_f8f6f4 v[40:43], v[16:23], v[156:163], v[192:195]
	v_mfma_f32_16x16x128_f8f6f4 v[28:31], v[0:7], v[164:171], v[202:205]
	v_mfma_f32_16x16x128_f8f6f4 v[24:27], v[16:23], v[164:171], v[206:209]
	v_mfma_f32_16x16x128_f8f6f4 v[12:15], v[0:7], v[172:179], v[218:221]
	v_mfma_f32_16x16x128_f8f6f4 v[8:11], v[16:23], v[172:179], v[222:225]
	s_setprio 0
	s_setprio 1
	v_mfma_f32_16x16x128_f8f6f4 v[52:55], v[140:147], v[32:39], v[52:55]
	v_mfma_f32_16x16x128_f8f6f4 v[48:51], v[148:155], v[32:39], v[48:51]
	v_mfma_f32_16x16x128_f8f6f4 v[36:39], v[140:147], v[156:163], v[226:229]
	v_mfma_f32_16x16x128_f8f6f4 v[32:35], v[148:155], v[156:163], v[230:233]
	v_mfma_f32_16x16x128_f8f6f4 v[20:23], v[140:147], v[164:171], v[234:237]
	v_mfma_f32_16x16x128_f8f6f4 v[16:19], v[148:155], v[164:171], v[238:241]
	v_mfma_f32_16x16x128_f8f6f4 v[4:7], v[140:147], v[172:179], v[242:245]
	v_mfma_f32_16x16x128_f8f6f4 v[0:3], v[148:155], v[172:179], v[246:249]
	s_setprio 0
	s_barrier
	s_add_i32 s47, s47, 2
	s_add_u32 s17, s17, 0x100
	s_addc_u32 s23, s23, 0
	s_cmp_gt_u32 s47, 29
	s_cbranch_scc0 .LBB0_1078
	s_and_b64 vcc, exec, s[10:11]
	s_cbranch_vccz .LBB0_1081
	s_barrier
; __device__ __forceinline__ float bflo(unsigned w) { return __uint_as_float(w << 16); }
; __device__ __forceinline__ float bfhi(unsigned w) { return __uint_as_float(w & 0xffff0000u); }
; __device__ __forceinline__ u32x4 pack8(f32x4 a, f32x4 b) { u32x4 w; w[0] = cvt_pk_bf16(a[0], a[1]); w[1] = cvt_pk_bf16(a[2], a[3]); w[2] = cvt_pk_bf16(b[0], b[1]); w[3] = cvt_pk_bf16(b[2], b[3]); return w; }
;   __device__ __forceinline__ void operator()(const Acc& acc, const GUnit& u, int wr, int wc, int fr, int fq) const {
;     const int row0 = u.pm * 256 + wr * 64 + fr; const int col0 = u.pn * 256 + wc * 32 + 8 * fq;
; #pragma unroll
;     for (int ai = 0; ai < 2; ++ai)
; #pragma unroll
;       for (int m = 0; m < 4; ++m) {
;         const int row = row0 + ai * 128 + m * 16; const size_t off = (size_t)row * 2048 + col0; float s = 0.f;
; #pragma unroll
;         for (int bj = 0; bj < 2; ++bj) {
;           f32x4 r0, r1;
;           if (R) { r0 = *(const f32x4*)(R + off + bj * 128); r1 = *(const f32x4*)(R + off + bj * 128 + 4); }
;           else { const u32x4 rw = *(const u32x4*)(RB + (size_t)row * ldrb + col0 + bj * 128);
;             r0 = (f32x4){bflo(rw[0]), bfhi(rw[0]), bflo(rw[1]), bfhi(rw[1])}; r1 = (f32x4){bflo(rw[2]), bfhi(rw[2]), bflo(rw[3]), bfhi(rw[3])}; }
;           const f32x4 h0 = r0 + acc[ai][bj][m][0] * osc, h1 = r1 + acc[ai][bj][m][1] * osc;
;           if (H) { *(f32x4*)(H + off + bj * 128) = h0; *(f32x4*)(H + off + bj * 128 + 4) = h1; }
;           if (HB) *(u32x4*)(HB + (size_t)row * ldhb + col0 + bj * 128) = pack8(h0, h1);
;           s += h0[0] * h0[0] + h0[1] * h0[1] + h0[2] * h0[2] + h0[3] * h0[3] + h1[0] * h1[0] + h1[1] * h1[1] + h1[2] * h1[2] + h1[3] * h1[3];
.LBB0_1081:
	v_mov_b32_e32 v132, v200
	s_lshl_b32 s22, s22, 8
	v_readfirstlane_b32 s17, v132
	s_ashr_i32 s23, s17, 2
	s_andn2_b32 s23, s23, 63
	s_add_i32 s23, s23, s22
	s_lshl_b32 s22, s46, 8
	s_and_b32 s17, s17, 0xc0
	s_or_b32 s17, s17, s22
	v_bfe_u32 v196, v132, 4, 2
	v_and_or_b32 v192, v132, 15, s23
	v_and_or_b32 v194, v132, 7, s23
	v_and_b32_e32 v197, 8, v132
	v_cmp_eq_u32_e32 vcc, 0, v196
	v_mov_b32_e32 v193, 0
	v_readlane_b32 s48, v254, 0
	v_readlane_b32 s49, v254, 1
	v_lshl_add_u64 v[198:199], v[192:193], 2, s[8:9]
	v_mov_b32_e32 v195, 0
	v_lshlrev_b64 v[132:133], 13, v[194:195]
	s_lshl_b32 s64, s17, 2
	v_lshl_or_b32 v188, v196, 5, s64
	v_lshl_or_b32 v188, v197, 1, v188
	v_mov_b32_e32 v189, 0
	v_lshl_add_u64 v[132:133], s[48:49], 0, v[132:133]
	v_lshl_add_u64 v[132:133], v[132:133], 0, v[188:189]
	v_mov_b64_e32 v[134:135], s[92:93]
	s_lshl_b32 s64, s17, 1
	v_mad_i64_i32 v[134:135], s[22:23], v194, s44, v[134:135]
	v_lshl_or_b32 v188, v196, 4, s64
	v_lshl_or_b32 v188, v197, 3, v188
	s_nop 0
	v_lshl_add_u64 v[134:135], v[134:135], 0, v[188:189]
	s_mov_b64 s[66:67], 0x10000
	v_lshl_add_u64 v[194:195], v[132:133], 0, s[66:67]
	global_load_dwordx4 v[140:143], v[132:133], off
	global_load_dwordx4 v[144:147], v[194:195], off
	global_load_dwordx4 v[148:151], v[132:133], off offset:128
	global_load_dwordx4 v[152:155], v[194:195], off offset:128
	s_mov_b64 s[64:65], 0x20000
	v_lshl_add_u64 v[192:193], v[132:133], 0, s[64:65]
	s_mov_b64 s[66:67], 0x30000
	v_lshl_add_u64 v[194:195], v[132:133], 0, s[66:67]
	global_load_dwordx4 v[156:159], v[192:193], off
	global_load_dwordx4 v[160:163], v[194:195], off
	global_load_dwordx4 v[164:167], v[192:193], off offset:128
	global_load_dwordx4 v[168:171], v[194:195], off offset:128
	s_mov_b64 s[64:65], 0x40000
	v_lshl_add_u64 v[192:193], v[132:133], 0, s[64:65]
	s_mov_b64 s[66:67], 0x50000
	v_lshl_add_u64 v[194:195], v[132:133], 0, s[66:67]
	global_load_dwordx4 v[172:175], v[192:193], off
	global_load_dwordx4 v[176:179], v[194:195], off
	global_load_dwordx4 v[180:183], v[192:193], off offset:128
	global_load_dwordx4 v[184:187], v[194:195], off offset:128
	s_mov_b64 s[64:65], 0x60000
	v_lshl_add_u64 v[192:193], v[132:133], 0, s[64:65]
	s_mov_b64 s[66:67], 0x70000
	v_lshl_add_u64 v[194:195], v[132:133], 0, s[66:67]
	global_load_dwordx4 v[202:205], v[192:193], off
	global_load_dwordx4 v[206:209], v[194:195], off
	global_load_dwordx4 v[210:213], v[192:193], off offset:128
	global_load_dwordx4 v[214:217], v[194:195], off offset:128
	s_mov_b64 s[64:65], 0x100000
	v_lshl_add_u64 v[192:193], v[132:133], 0, s[64:65]
	s_mov_b64 s[66:67], 0x110000
	v_lshl_add_u64 v[194:195], v[132:133], 0, s[66:67]
	global_load_dwordx4 v[218:221], v[192:193], off
	global_load_dwordx4 v[222:225], v[194:195], off
	global_load_dwordx4 v[226:229], v[192:193], off offset:128
	global_load_dwordx4 v[230:233], v[194:195], off offset:128
	s_mov_b64 s[64:65], 0x120000
	v_lshl_add_u64 v[192:193], v[132:133], 0, s[64:65]
	s_mov_b64 s[66:67], 0x130000
	v_lshl_add_u64 v[194:195], v[132:133], 0, s[66:67]
	global_load_dwordx4 v[234:237], v[192:193], off
	global_load_dwordx4 v[238:241], v[194:195], off
	global_load_dwordx4 v[242:245], v[192:193], off offset:128
	global_load_dwordx4 v[246:249], v[194:195], off offset:128
	s_waitcnt vmcnt(20)
	v_mov_b32_e32 v188, v140
	v_mov_b32_e32 v189, v141
	v_mov_b32_e32 v190, v142
	v_mov_b32_e32 v191, v143
	v_mov_b32_dpp v140, v144 row_ror:8 row_mask:0xf bank_mask:0xc
	v_mov_b32_dpp v141, v145 row_ror:8 row_mask:0xf bank_mask:0xc
	v_mov_b32_dpp v142, v146 row_ror:8 row_mask:0xf bank_mask:0xc
	v_mov_b32_dpp v143, v147 row_ror:8 row_mask:0xf bank_mask:0xc
	v_mov_b32_dpp v144, v188 row_ror:8 row_mask:0xf bank_mask:0x3
	v_mov_b32_dpp v145, v189 row_ror:8 row_mask:0xf bank_mask:0x3
	v_mov_b32_dpp v146, v190 row_ror:8 row_mask:0xf bank_mask:0x3
	v_mov_b32_dpp v147, v191 row_ror:8 row_mask:0xf bank_mask:0x3
	v_pk_fma_f32 v[140:141], v[124:125], s[12:13], v[140:141] op_sel_hi:[1,0,1]
	v_pk_fma_f32 v[142:143], v[126:127], s[12:13], v[142:143] op_sel_hi:[1,0,1]
	v_pk_fma_f32 v[144:145], v[120:121], s[12:13], v[144:145] op_sel_hi:[1,0,1]
	v_pk_fma_f32 v[146:147], v[122:123], s[12:13], v[146:147] op_sel_hi:[1,0,1]
	v_cvt_pk_bf16_f32 v120, v140, v141
	v_cvt_pk_bf16_f32 v121, v142, v143
	v_cvt_pk_bf16_f32 v122, v144, v145
	v_cvt_pk_bf16_f32 v123, v146, v147
	v_mul_f32_e32 v196, v140, v140
	v_fmac_f32_e32 v196, v141, v141
	v_fmac_f32_e32 v196, v142, v142
	v_fmac_f32_e32 v196, v143, v143
	v_fmac_f32_e32 v196, v144, v144
	v_fmac_f32_e32 v196, v145, v145
	v_fmac_f32_e32 v196, v146, v146
	v_fmac_f32_e32 v196, v147, v147
	v_mov_b32_e32 v188, v148
	v_mov_b32_e32 v189, v149
	v_mov_b32_e32 v190, v150
	v_mov_b32_e32 v191, v151
	v_mov_b32_dpp v148, v152 row_ror:8 row_mask:0xf bank_mask:0xc
	v_mov_b32_dpp v149, v153 row_ror:8 row_mask:0xf bank_mask:0xc
	v_mov_b32_dpp v150, v154 row_ror:8 row_mask:0xf bank_mask:0xc
	v_mov_b32_dpp v151, v155 row_ror:8 row_mask:0xf bank_mask:0xc
	v_mov_b32_dpp v152, v188 row_ror:8 row_mask:0xf bank_mask:0x3
	v_mov_b32_dpp v153, v189 row_ror:8 row_mask:0xf bank_mask:0x3
	v_mov_b32_dpp v154, v190 row_ror:8 row_mask:0xf bank_mask:0x3
	v_mov_b32_dpp v155, v191 row_ror:8 row_mask:0xf bank_mask:0x3
	v_pk_fma_f32 v[148:149], v[116:117], s[12:13], v[148:149] op_sel_hi:[1,0,1]
	v_pk_fma_f32 v[150:151], v[118:119], s[12:13], v[150:151] op_sel_hi:[1,0,1]
	v_pk_fma_f32 v[152:153], v[112:113], s[12:13], v[152:153] op_sel_hi:[1,0,1]
	v_pk_fma_f32 v[154:155], v[114:115], s[12:13], v[154:155] op_sel_hi:[1,0,1]
	v_cvt_pk_bf16_f32 v112, v148, v149
	v_cvt_pk_bf16_f32 v113, v150, v151
	v_cvt_pk_bf16_f32 v114, v152, v153
; __device__ __forceinline__ float bflo(unsigned w) { return __uint_as_float(w << 16); }
; __device__ __forceinline__ float bfhi(unsigned w) { return __uint_as_float(w & 0xffff0000u); }
; __device__ __forceinline__ u32x4 pack8(f32x4 a, f32x4 b) { u32x4 w; w[0] = cvt_pk_bf16(a[0], a[1]); w[1] = cvt_pk_bf16(a[2], a[3]); w[2] = cvt_pk_bf16(b[0], b[1]); w[3] = cvt_pk_bf16(b[2], b[3]); return w; }
; __device__ __forceinline__ float psum16(float x) { const u32x2s r = __builtin_amdgcn_permlane16_swap(__float_as_uint(x), __float_as_uint(x), false, false); return __uint_as_float(r[0]) + __uint_as_float(r[1]); }
; __device__ __forceinline__ float psum32(float x) { const u32x2s r = __builtin_amdgcn_permlane32_swap(__float_as_uint(x), __float_as_uint(x), false, false); return __uint_as_float(r[0]) + __uint_as_float(r[1]); }
;   __device__ __forceinline__ void operator()(const Acc& acc, const GUnit& u, int wr, int wc, int fr, int fq) const {
;     ...
;         const int row = row0 + ai * 128 + m * 16; const size_t off = (size_t)row * 2048 + col0; float s = 0.f;
; #pragma unroll
;         for (int bj = 0; bj < 2; ++bj) {
;           f32x4 r0, r1;
;           if (R) { r0 = *(const f32x4*)(R + off + bj * 128); r1 = *(const f32x4*)(R + off + bj * 128 + 4); }
;           else { const u32x4 rw = *(const u32x4*)(RB + (size_t)row * ldrb + col0 + bj * 128);
;             r0 = (f32x4){bflo(rw[0]), bfhi(rw[0]), bflo(rw[1]), bfhi(rw[1])}; r1 = (f32x4){bflo(rw[2]), bfhi(rw[2]), bflo(rw[3]), bfhi(rw[3])}; }
;           const f32x4 h0 = r0 + acc[ai][bj][m][0] * osc, h1 = r1 + acc[ai][bj][m][1] * osc;
;           if (H) { *(f32x4*)(H + off + bj * 128) = h0; *(f32x4*)(H + off + bj * 128 + 4) = h1; }
;           if (HB) *(u32x4*)(HB + (size_t)row * ldhb + col0 + bj * 128) = pack8(h0, h1);
;           s += h0[0] * h0[0] + h0[1] * h0[1] + h0[2] * h0[2] + h0[3] * h0[3] + h1[0] * h1[0] + h1[1] * h1[1] + h1[2] * h1[2] + h1[3] * h1[3];
;         }
;         s = psum32(psum16(s));
;         if (fq == 0) atomicAdd(ss + row, s);
	v_cvt_pk_bf16_f32 v115, v154, v155
	v_fmac_f32_e32 v196, v148, v148
	v_fmac_f32_e32 v196, v149, v149
	v_fmac_f32_e32 v196, v150, v150
	v_fmac_f32_e32 v196, v151, v151
	v_fmac_f32_e32 v196, v152, v152
	v_fmac_f32_e32 v196, v153, v153
	v_fmac_f32_e32 v196, v154, v154
	v_fmac_f32_e32 v196, v155, v155
	v_mov_b32_e32 v188, v120
	v_mov_b32_e32 v189, v121
	v_mov_b32_e32 v190, v122
	v_mov_b32_e32 v191, v123
	v_mov_b32_dpp v120, v112 row_ror:8 row_mask:0xf bank_mask:0xc
	v_mov_b32_dpp v121, v113 row_ror:8 row_mask:0xf bank_mask:0xc
	v_mov_b32_dpp v122, v114 row_ror:8 row_mask:0xf bank_mask:0xc
	v_mov_b32_dpp v123, v115 row_ror:8 row_mask:0xf bank_mask:0xc
	v_mov_b32_dpp v112, v188 row_ror:8 row_mask:0xf bank_mask:0x3
	v_mov_b32_dpp v113, v189 row_ror:8 row_mask:0xf bank_mask:0x3
	v_mov_b32_dpp v114, v190 row_ror:8 row_mask:0xf bank_mask:0x3
	v_mov_b32_dpp v115, v191 row_ror:8 row_mask:0xf bank_mask:0x3
	s_mov_b64 s[66:67], 0x8400
	v_lshl_add_u64 v[194:195], v[134:135], 0, s[66:67]
	global_store_dwordx4 v[134:135], v[120:123], off
	global_store_dwordx4 v[194:195], v[112:115], off
	v_mov_b32_e32 v197, v196
	s_nop 1
	v_permlane16_swap_b32_e32 v196, v197
	v_add_f32_e32 v196, v196, v197
	v_mov_b32_e32 v197, v196
	s_nop 1
	v_permlane32_swap_b32_e32 v196, v197
	s_and_saveexec_b64 s[22:23], vcc
	v_add_f32_e32 v196, v196, v197
	global_atomic_add_f32 v[198:199], v196, off
	s_or_b64 exec, exec, s[22:23]
	s_mov_b64 s[64:65], 0x140000
	v_lshl_add_u64 v[192:193], v[132:133], 0, s[64:65]
	s_mov_b64 s[66:67], 0x150000
	v_lshl_add_u64 v[194:195], v[132:133], 0, s[66:67]
	global_load_dwordx4 v[140:143], v[192:193], off
	global_load_dwordx4 v[144:147], v[194:195], off
	global_load_dwordx4 v[148:151], v[192:193], off offset:128
	global_load_dwordx4 v[152:155], v[194:195], off offset:128
	s_waitcnt vmcnt(20)
	v_mov_b32_e32 v188, v156
	v_mov_b32_e32 v189, v157
	v_mov_b32_e32 v190, v158
	v_mov_b32_e32 v191, v159
	v_mov_b32_dpp v156, v160 row_ror:8 row_mask:0xf bank_mask:0xc
	v_mov_b32_dpp v157, v161 row_ror:8 row_mask:0xf bank_mask:0xc
	v_mov_b32_dpp v158, v162 row_ror:8 row_mask:0xf bank_mask:0xc
	v_mov_b32_dpp v159, v163 row_ror:8 row_mask:0xf bank_mask:0xc
	v_mov_b32_dpp v160, v188 row_ror:8 row_mask:0xf bank_mask:0x3
	v_mov_b32_dpp v161, v189 row_ror:8 row_mask:0xf bank_mask:0x3
	v_mov_b32_dpp v162, v190 row_ror:8 row_mask:0xf bank_mask:0x3
	v_mov_b32_dpp v163, v191 row_ror:8 row_mask:0xf bank_mask:0x3
	v_pk_fma_f32 v[156:157], v[108:109], s[12:13], v[156:157] op_sel_hi:[1,0,1]
	v_pk_fma_f32 v[158:159], v[110:111], s[12:13], v[158:159] op_sel_hi:[1,0,1]
	v_pk_fma_f32 v[160:161], v[104:105], s[12:13], v[160:161] op_sel_hi:[1,0,1]
	v_pk_fma_f32 v[162:163], v[106:107], s[12:13], v[162:163] op_sel_hi:[1,0,1]
	v_cvt_pk_bf16_f32 v104, v156, v157
	v_cvt_pk_bf16_f32 v105, v158, v159
	v_cvt_pk_bf16_f32 v106, v160, v161
	v_cvt_pk_bf16_f32 v107, v162, v163
	v_mul_f32_e32 v196, v156, v156
	v_fmac_f32_e32 v196, v157, v157
	v_fmac_f32_e32 v196, v158, v158
	v_fmac_f32_e32 v196, v159, v159
	v_fmac_f32_e32 v196, v160, v160
	v_fmac_f32_e32 v196, v161, v161
	v_fmac_f32_e32 v196, v162, v162
	v_fmac_f32_e32 v196, v163, v163
	v_mov_b32_e32 v188, v164
	v_mov_b32_e32 v189, v165
	v_mov_b32_e32 v190, v166
	v_mov_b32_e32 v191, v167
	v_mov_b32_dpp v164, v168 row_ror:8 row_mask:0xf bank_mask:0xc
	v_mov_b32_dpp v165, v169 row_ror:8 row_mask:0xf bank_mask:0xc
	v_mov_b32_dpp v166, v170 row_ror:8 row_mask:0xf bank_mask:0xc
	v_mov_b32_dpp v167, v171 row_ror:8 row_mask:0xf bank_mask:0xc
	v_mov_b32_dpp v168, v188 row_ror:8 row_mask:0xf bank_mask:0x3
	v_mov_b32_dpp v169, v189 row_ror:8 row_mask:0xf bank_mask:0x3
	v_mov_b32_dpp v170, v190 row_ror:8 row_mask:0xf bank_mask:0x3
	v_mov_b32_dpp v171, v191 row_ror:8 row_mask:0xf bank_mask:0x3
	v_pk_fma_f32 v[164:165], v[100:101], s[12:13], v[164:165] op_sel_hi:[1,0,1]
	v_pk_fma_f32 v[166:167], v[102:103], s[12:13], v[166:167] op_sel_hi:[1,0,1]
	v_pk_fma_f32 v[168:169], v[96:97], s[12:13], v[168:169] op_sel_hi:[1,0,1]
	v_pk_fma_f32 v[170:171], v[98:99], s[12:13], v[170:171] op_sel_hi:[1,0,1]
	v_cvt_pk_bf16_f32 v96, v164, v165
	v_cvt_pk_bf16_f32 v97, v166, v167
	v_cvt_pk_bf16_f32 v98, v168, v169
	v_cvt_pk_bf16_f32 v99, v170, v171
	v_fmac_f32_e32 v196, v164, v164
	v_fmac_f32_e32 v196, v165, v165
	v_fmac_f32_e32 v196, v166, v166
	v_fmac_f32_e32 v196, v167, v167
	v_fmac_f32_e32 v196, v168, v168
	v_fmac_f32_e32 v196, v169, v169
	v_fmac_f32_e32 v196, v170, v170
	v_fmac_f32_e32 v196, v171, v171
	v_mov_b32_e32 v188, v104
	v_mov_b32_e32 v189, v105
	v_mov_b32_e32 v190, v106
	v_mov_b32_e32 v191, v107
	v_mov_b32_dpp v104, v96 row_ror:8 row_mask:0xf bank_mask:0xc
	v_mov_b32_dpp v105, v97 row_ror:8 row_mask:0xf bank_mask:0xc
	v_mov_b32_dpp v106, v98 row_ror:8 row_mask:0xf bank_mask:0xc
	v_mov_b32_dpp v107, v99 row_ror:8 row_mask:0xf bank_mask:0xc
	v_mov_b32_dpp v96, v188 row_ror:8 row_mask:0xf bank_mask:0x3
	v_mov_b32_dpp v97, v189 row_ror:8 row_mask:0xf bank_mask:0x3
	v_mov_b32_dpp v98, v190 row_ror:8 row_mask:0xf bank_mask:0x3
	v_mov_b32_dpp v99, v191 row_ror:8 row_mask:0xf bank_mask:0x3
	s_mov_b64 s[64:65], 0x10800
	v_lshl_add_u64 v[192:193], v[134:135], 0, s[64:65]
	s_mov_b64 s[66:67], 0x18c00
	v_lshl_add_u64 v[194:195], v[134:135], 0, s[66:67]
	global_store_dwordx4 v[192:193], v[104:107], off
	global_store_dwordx4 v[194:195], v[96:99], off
	v_mov_b32_e32 v197, v196
	s_nop 1
	v_permlane16_swap_b32_e32 v196, v197
	v_add_f32_e32 v196, v196, v197
	v_mov_b32_e32 v197, v196
	s_nop 1
	v_permlane32_swap_b32_e32 v196, v197
	s_and_saveexec_b64 s[22:23], vcc
	v_add_f32_e32 v196, v196, v197
	global_atomic_add_f32 v[198:199], v196, off offset:64
	s_or_b64 exec, exec, s[22:23]
	s_mov_b64 s[64:65], 0x160000
	v_lshl_add_u64 v[192:193], v[132:133], 0, s[64:65]
	s_mov_b64 s[66:67], 0x170000
	v_lshl_add_u64 v[194:195], v[132:133], 0, s[66:67]
	global_load_dwordx4 v[156:159], v[192:193], off
	global_load_dwordx4 v[160:163], v[194:195], off
	global_load_dwordx4 v[164:167], v[192:193], off offset:128
	global_load_dwordx4 v[168:171], v[194:195], off offset:128
	s_waitcnt vmcnt(20)
; __device__ __forceinline__ float bflo(unsigned w) { return __uint_as_float(w << 16); }
; __device__ __forceinline__ float bfhi(unsigned w) { return __uint_as_float(w & 0xffff0000u); }
; __device__ __forceinline__ u32x4 pack8(f32x4 a, f32x4 b) { u32x4 w; w[0] = cvt_pk_bf16(a[0], a[1]); w[1] = cvt_pk_bf16(a[2], a[3]); w[2] = cvt_pk_bf16(b[0], b[1]); w[3] = cvt_pk_bf16(b[2], b[3]); return w; }
; __device__ __forceinline__ float psum16(float x) { const u32x2s r = __builtin_amdgcn_permlane16_swap(__float_as_uint(x), __float_as_uint(x), false, false); return __uint_as_float(r[0]) + __uint_as_float(r[1]); }
; __device__ __forceinline__ float psum32(float x) { const u32x2s r = __builtin_amdgcn_permlane32_swap(__float_as_uint(x), __float_as_uint(x), false, false); return __uint_as_float(r[0]) + __uint_as_float(r[1]); }
;   __device__ __forceinline__ void operator()(const Acc& acc, const GUnit& u, int wr, int wc, int fr, int fq) const {
;     ...
;         const int row = row0 + ai * 128 + m * 16; const size_t off = (size_t)row * 2048 + col0; float s = 0.f;
; #pragma unroll
;         for (int bj = 0; bj < 2; ++bj) {
;           f32x4 r0, r1;
;           if (R) { r0 = *(const f32x4*)(R + off + bj * 128); r1 = *(const f32x4*)(R + off + bj * 128 + 4); }
;           else { const u32x4 rw = *(const u32x4*)(RB + (size_t)row * ldrb + col0 + bj * 128);
;             r0 = (f32x4){bflo(rw[0]), bfhi(rw[0]), bflo(rw[1]), bfhi(rw[1])}; r1 = (f32x4){bflo(rw[2]), bfhi(rw[2]), bflo(rw[3]), bfhi(rw[3])}; }
;           const f32x4 h0 = r0 + acc[ai][bj][m][0] * osc, h1 = r1 + acc[ai][bj][m][1] * osc;
;           if (H) { *(f32x4*)(H + off + bj * 128) = h0; *(f32x4*)(H + off + bj * 128 + 4) = h1; }
;           if (HB) *(u32x4*)(HB + (size_t)row * ldhb + col0 + bj * 128) = pack8(h0, h1);
;           s += h0[0] * h0[0] + h0[1] * h0[1] + h0[2] * h0[2] + h0[3] * h0[3] + h1[0] * h1[0] + h1[1] * h1[1] + h1[2] * h1[2] + h1[3] * h1[3];
;         }
;         s = psum32(psum16(s));
;         if (fq == 0) atomicAdd(ss + row, s);
	v_mov_b32_e32 v188, v172
	v_mov_b32_e32 v189, v173
	v_mov_b32_e32 v190, v174
	v_mov_b32_e32 v191, v175
	v_mov_b32_dpp v172, v176 row_ror:8 row_mask:0xf bank_mask:0xc
	v_mov_b32_dpp v173, v177 row_ror:8 row_mask:0xf bank_mask:0xc
	v_mov_b32_dpp v174, v178 row_ror:8 row_mask:0xf bank_mask:0xc
	v_mov_b32_dpp v175, v179 row_ror:8 row_mask:0xf bank_mask:0xc
	v_mov_b32_dpp v176, v188 row_ror:8 row_mask:0xf bank_mask:0x3
	v_mov_b32_dpp v177, v189 row_ror:8 row_mask:0xf bank_mask:0x3
	v_mov_b32_dpp v178, v190 row_ror:8 row_mask:0xf bank_mask:0x3
	v_mov_b32_dpp v179, v191 row_ror:8 row_mask:0xf bank_mask:0x3
	v_pk_fma_f32 v[172:173], v[92:93], s[12:13], v[172:173] op_sel_hi:[1,0,1]
	v_pk_fma_f32 v[174:175], v[94:95], s[12:13], v[174:175] op_sel_hi:[1,0,1]
	v_pk_fma_f32 v[176:177], v[88:89], s[12:13], v[176:177] op_sel_hi:[1,0,1]
	v_pk_fma_f32 v[178:179], v[90:91], s[12:13], v[178:179] op_sel_hi:[1,0,1]
	v_cvt_pk_bf16_f32 v88, v172, v173
	v_cvt_pk_bf16_f32 v89, v174, v175
	v_cvt_pk_bf16_f32 v90, v176, v177
	v_cvt_pk_bf16_f32 v91, v178, v179
	v_mul_f32_e32 v196, v172, v172
	v_fmac_f32_e32 v196, v173, v173
	v_fmac_f32_e32 v196, v174, v174
	v_fmac_f32_e32 v196, v175, v175
	v_fmac_f32_e32 v196, v176, v176
	v_fmac_f32_e32 v196, v177, v177
	v_fmac_f32_e32 v196, v178, v178
	v_fmac_f32_e32 v196, v179, v179
	v_mov_b32_e32 v188, v180
	v_mov_b32_e32 v189, v181
	v_mov_b32_e32 v190, v182
	v_mov_b32_e32 v191, v183
	v_mov_b32_dpp v180, v184 row_ror:8 row_mask:0xf bank_mask:0xc
	v_mov_b32_dpp v181, v185 row_ror:8 row_mask:0xf bank_mask:0xc
	v_mov_b32_dpp v182, v186 row_ror:8 row_mask:0xf bank_mask:0xc
	v_mov_b32_dpp v183, v187 row_ror:8 row_mask:0xf bank_mask:0xc
	v_mov_b32_dpp v184, v188 row_ror:8 row_mask:0xf bank_mask:0x3
	v_mov_b32_dpp v185, v189 row_ror:8 row_mask:0xf bank_mask:0x3
	v_mov_b32_dpp v186, v190 row_ror:8 row_mask:0xf bank_mask:0x3
	v_mov_b32_dpp v187, v191 row_ror:8 row_mask:0xf bank_mask:0x3
	v_pk_fma_f32 v[180:181], v[84:85], s[12:13], v[180:181] op_sel_hi:[1,0,1]
	v_pk_fma_f32 v[182:183], v[86:87], s[12:13], v[182:183] op_sel_hi:[1,0,1]
	v_pk_fma_f32 v[184:185], v[80:81], s[12:13], v[184:185] op_sel_hi:[1,0,1]
	v_pk_fma_f32 v[186:187], v[82:83], s[12:13], v[186:187] op_sel_hi:[1,0,1]
	v_cvt_pk_bf16_f32 v80, v180, v181
	v_cvt_pk_bf16_f32 v81, v182, v183
	v_cvt_pk_bf16_f32 v82, v184, v185
	v_cvt_pk_bf16_f32 v83, v186, v187
	v_fmac_f32_e32 v196, v180, v180
	v_fmac_f32_e32 v196, v181, v181
	v_fmac_f32_e32 v196, v182, v182
	v_fmac_f32_e32 v196, v183, v183
	v_fmac_f32_e32 v196, v184, v184
	v_fmac_f32_e32 v196, v185, v185
	v_fmac_f32_e32 v196, v186, v186
	v_fmac_f32_e32 v196, v187, v187
	v_mov_b32_e32 v188, v88
	v_mov_b32_e32 v189, v89
	v_mov_b32_e32 v190, v90
	v_mov_b32_e32 v191, v91
	v_mov_b32_dpp v88, v80 row_ror:8 row_mask:0xf bank_mask:0xc
	v_mov_b32_dpp v89, v81 row_ror:8 row_mask:0xf bank_mask:0xc
	v_mov_b32_dpp v90, v82 row_ror:8 row_mask:0xf bank_mask:0xc
	v_mov_b32_dpp v91, v83 row_ror:8 row_mask:0xf bank_mask:0xc
	v_mov_b32_dpp v80, v188 row_ror:8 row_mask:0xf bank_mask:0x3
	v_mov_b32_dpp v81, v189 row_ror:8 row_mask:0xf bank_mask:0x3
	v_mov_b32_dpp v82, v190 row_ror:8 row_mask:0xf bank_mask:0x3
	v_mov_b32_dpp v83, v191 row_ror:8 row_mask:0xf bank_mask:0x3
	s_mov_b64 s[64:65], 0x21000
	v_lshl_add_u64 v[192:193], v[134:135], 0, s[64:65]
	s_mov_b64 s[66:67], 0x29400
	v_lshl_add_u64 v[194:195], v[134:135], 0, s[66:67]
	global_store_dwordx4 v[192:193], v[88:91], off
	global_store_dwordx4 v[194:195], v[80:83], off
	v_mov_b32_e32 v197, v196
	s_nop 1
	v_permlane16_swap_b32_e32 v196, v197
	v_add_f32_e32 v196, v196, v197
	v_mov_b32_e32 v197, v196
	s_nop 1
	v_permlane32_swap_b32_e32 v196, v197
	s_and_saveexec_b64 s[22:23], vcc
	v_add_f32_e32 v196, v196, v197
	global_atomic_add_f32 v[198:199], v196, off offset:128
	s_or_b64 exec, exec, s[22:23]
	s_waitcnt vmcnt(16)
	v_mov_b32_e32 v188, v202
	v_mov_b32_e32 v189, v203
	v_mov_b32_e32 v190, v204
	v_mov_b32_e32 v191, v205
	v_mov_b32_dpp v202, v206 row_ror:8 row_mask:0xf bank_mask:0xc
	v_mov_b32_dpp v203, v207 row_ror:8 row_mask:0xf bank_mask:0xc
	v_mov_b32_dpp v204, v208 row_ror:8 row_mask:0xf bank_mask:0xc
	v_mov_b32_dpp v205, v209 row_ror:8 row_mask:0xf bank_mask:0xc
	v_mov_b32_dpp v206, v188 row_ror:8 row_mask:0xf bank_mask:0x3
	v_mov_b32_dpp v207, v189 row_ror:8 row_mask:0xf bank_mask:0x3
	v_mov_b32_dpp v208, v190 row_ror:8 row_mask:0xf bank_mask:0x3
	v_mov_b32_dpp v209, v191 row_ror:8 row_mask:0xf bank_mask:0x3
	v_pk_fma_f32 v[202:203], v[76:77], s[12:13], v[202:203] op_sel_hi:[1,0,1]
	v_pk_fma_f32 v[204:205], v[78:79], s[12:13], v[204:205] op_sel_hi:[1,0,1]
	v_pk_fma_f32 v[206:207], v[72:73], s[12:13], v[206:207] op_sel_hi:[1,0,1]
	v_pk_fma_f32 v[208:209], v[74:75], s[12:13], v[208:209] op_sel_hi:[1,0,1]
	v_cvt_pk_bf16_f32 v72, v202, v203
	v_cvt_pk_bf16_f32 v73, v204, v205
	v_cvt_pk_bf16_f32 v74, v206, v207
	v_cvt_pk_bf16_f32 v75, v208, v209
	v_mul_f32_e32 v196, v202, v202
	v_fmac_f32_e32 v196, v203, v203
	v_fmac_f32_e32 v196, v204, v204
	v_fmac_f32_e32 v196, v205, v205
	v_fmac_f32_e32 v196, v206, v206
	v_fmac_f32_e32 v196, v207, v207
	v_fmac_f32_e32 v196, v208, v208
	v_fmac_f32_e32 v196, v209, v209
	v_mov_b32_e32 v188, v210
	v_mov_b32_e32 v189, v211
	v_mov_b32_e32 v190, v212
	v_mov_b32_e32 v191, v213
	v_mov_b32_dpp v210, v214 row_ror:8 row_mask:0xf bank_mask:0xc
	v_mov_b32_dpp v211, v215 row_ror:8 row_mask:0xf bank_mask:0xc
	v_mov_b32_dpp v212, v216 row_ror:8 row_mask:0xf bank_mask:0xc
	v_mov_b32_dpp v213, v217 row_ror:8 row_mask:0xf bank_mask:0xc
	v_mov_b32_dpp v214, v188 row_ror:8 row_mask:0xf bank_mask:0x3
	v_mov_b32_dpp v215, v189 row_ror:8 row_mask:0xf bank_mask:0x3
; __device__ __forceinline__ float bflo(unsigned w) { return __uint_as_float(w << 16); }
; __device__ __forceinline__ float bfhi(unsigned w) { return __uint_as_float(w & 0xffff0000u); }
; __device__ __forceinline__ u32x4 pack8(f32x4 a, f32x4 b) { u32x4 w; w[0] = cvt_pk_bf16(a[0], a[1]); w[1] = cvt_pk_bf16(a[2], a[3]); w[2] = cvt_pk_bf16(b[0], b[1]); w[3] = cvt_pk_bf16(b[2], b[3]); return w; }
; __device__ __forceinline__ float psum16(float x) { const u32x2s r = __builtin_amdgcn_permlane16_swap(__float_as_uint(x), __float_as_uint(x), false, false); return __uint_as_float(r[0]) + __uint_as_float(r[1]); }
; __device__ __forceinline__ float psum32(float x) { const u32x2s r = __builtin_amdgcn_permlane32_swap(__float_as_uint(x), __float_as_uint(x), false, false); return __uint_as_float(r[0]) + __uint_as_float(r[1]); }
;   __device__ __forceinline__ void operator()(const Acc& acc, const GUnit& u, int wr, int wc, int fr, int fq) const {
;     ...
;         const int row = row0 + ai * 128 + m * 16; const size_t off = (size_t)row * 2048 + col0; float s = 0.f;
; #pragma unroll
;         for (int bj = 0; bj < 2; ++bj) {
;           f32x4 r0, r1;
;           if (R) { r0 = *(const f32x4*)(R + off + bj * 128); r1 = *(const f32x4*)(R + off + bj * 128 + 4); }
;           else { const u32x4 rw = *(const u32x4*)(RB + (size_t)row * ldrb + col0 + bj * 128);
;             r0 = (f32x4){bflo(rw[0]), bfhi(rw[0]), bflo(rw[1]), bfhi(rw[1])}; r1 = (f32x4){bflo(rw[2]), bfhi(rw[2]), bflo(rw[3]), bfhi(rw[3])}; }
;           const f32x4 h0 = r0 + acc[ai][bj][m][0] * osc, h1 = r1 + acc[ai][bj][m][1] * osc;
;           if (H) { *(f32x4*)(H + off + bj * 128) = h0; *(f32x4*)(H + off + bj * 128 + 4) = h1; }
;           if (HB) *(u32x4*)(HB + (size_t)row * ldhb + col0 + bj * 128) = pack8(h0, h1);
;           s += h0[0] * h0[0] + h0[1] * h0[1] + h0[2] * h0[2] + h0[3] * h0[3] + h1[0] * h1[0] + h1[1] * h1[1] + h1[2] * h1[2] + h1[3] * h1[3];
;         }
;         s = psum32(psum16(s));
;         if (fq == 0) atomicAdd(ss + row, s);
	v_mov_b32_dpp v216, v190 row_ror:8 row_mask:0xf bank_mask:0x3
	v_mov_b32_dpp v217, v191 row_ror:8 row_mask:0xf bank_mask:0x3
	v_pk_fma_f32 v[210:211], v[68:69], s[12:13], v[210:211] op_sel_hi:[1,0,1]
	v_pk_fma_f32 v[212:213], v[70:71], s[12:13], v[212:213] op_sel_hi:[1,0,1]
	v_pk_fma_f32 v[214:215], v[64:65], s[12:13], v[214:215] op_sel_hi:[1,0,1]
	v_pk_fma_f32 v[216:217], v[66:67], s[12:13], v[216:217] op_sel_hi:[1,0,1]
	v_cvt_pk_bf16_f32 v64, v210, v211
	v_cvt_pk_bf16_f32 v65, v212, v213
	v_cvt_pk_bf16_f32 v66, v214, v215
	v_cvt_pk_bf16_f32 v67, v216, v217
	v_fmac_f32_e32 v196, v210, v210
	v_fmac_f32_e32 v196, v211, v211
	v_fmac_f32_e32 v196, v212, v212
	v_fmac_f32_e32 v196, v213, v213
	v_fmac_f32_e32 v196, v214, v214
	v_fmac_f32_e32 v196, v215, v215
	v_fmac_f32_e32 v196, v216, v216
	v_fmac_f32_e32 v196, v217, v217
	v_mov_b32_e32 v188, v72
	v_mov_b32_e32 v189, v73
	v_mov_b32_e32 v190, v74
	v_mov_b32_e32 v191, v75
	v_mov_b32_dpp v72, v64 row_ror:8 row_mask:0xf bank_mask:0xc
	v_mov_b32_dpp v73, v65 row_ror:8 row_mask:0xf bank_mask:0xc
	v_mov_b32_dpp v74, v66 row_ror:8 row_mask:0xf bank_mask:0xc
	v_mov_b32_dpp v75, v67 row_ror:8 row_mask:0xf bank_mask:0xc
	v_mov_b32_dpp v64, v188 row_ror:8 row_mask:0xf bank_mask:0x3
	v_mov_b32_dpp v65, v189 row_ror:8 row_mask:0xf bank_mask:0x3
	v_mov_b32_dpp v66, v190 row_ror:8 row_mask:0xf bank_mask:0x3
	v_mov_b32_dpp v67, v191 row_ror:8 row_mask:0xf bank_mask:0x3
	s_mov_b64 s[64:65], 0x31800
	v_lshl_add_u64 v[192:193], v[134:135], 0, s[64:65]
	s_mov_b64 s[66:67], 0x39c00
	v_lshl_add_u64 v[194:195], v[134:135], 0, s[66:67]
	global_store_dwordx4 v[192:193], v[72:75], off
	global_store_dwordx4 v[194:195], v[64:67], off
	v_mov_b32_e32 v197, v196
	s_nop 1
	v_permlane16_swap_b32_e32 v196, v197
	v_add_f32_e32 v196, v196, v197
	v_mov_b32_e32 v197, v196
	s_nop 1
	v_permlane32_swap_b32_e32 v196, v197
	s_and_saveexec_b64 s[22:23], vcc
	v_add_f32_e32 v196, v196, v197
	global_atomic_add_f32 v[198:199], v196, off offset:192
	s_or_b64 exec, exec, s[22:23]
	s_waitcnt vmcnt(12)
	v_mov_b32_e32 v188, v218
	v_mov_b32_e32 v189, v219
	v_mov_b32_e32 v190, v220
	v_mov_b32_e32 v191, v221
	v_mov_b32_dpp v218, v222 row_ror:8 row_mask:0xf bank_mask:0xc
	v_mov_b32_dpp v219, v223 row_ror:8 row_mask:0xf bank_mask:0xc
	v_mov_b32_dpp v220, v224 row_ror:8 row_mask:0xf bank_mask:0xc
	v_mov_b32_dpp v221, v225 row_ror:8 row_mask:0xf bank_mask:0xc
	v_mov_b32_dpp v222, v188 row_ror:8 row_mask:0xf bank_mask:0x3
	v_mov_b32_dpp v223, v189 row_ror:8 row_mask:0xf bank_mask:0x3
	v_mov_b32_dpp v224, v190 row_ror:8 row_mask:0xf bank_mask:0x3
	v_mov_b32_dpp v225, v191 row_ror:8 row_mask:0xf bank_mask:0x3
	v_pk_fma_f32 v[218:219], v[60:61], s[12:13], v[218:219] op_sel_hi:[1,0,1]
	v_pk_fma_f32 v[220:221], v[62:63], s[12:13], v[220:221] op_sel_hi:[1,0,1]
	v_pk_fma_f32 v[222:223], v[56:57], s[12:13], v[222:223] op_sel_hi:[1,0,1]
	v_pk_fma_f32 v[224:225], v[58:59], s[12:13], v[224:225] op_sel_hi:[1,0,1]
	v_cvt_pk_bf16_f32 v56, v218, v219
	v_cvt_pk_bf16_f32 v57, v220, v221
	v_cvt_pk_bf16_f32 v58, v222, v223
	v_cvt_pk_bf16_f32 v59, v224, v225
	v_mul_f32_e32 v196, v218, v218
	v_fmac_f32_e32 v196, v219, v219
	v_fmac_f32_e32 v196, v220, v220
	v_fmac_f32_e32 v196, v221, v221
	v_fmac_f32_e32 v196, v222, v222
	v_fmac_f32_e32 v196, v223, v223
	v_fmac_f32_e32 v196, v224, v224
	v_fmac_f32_e32 v196, v225, v225
	v_mov_b32_e32 v188, v226
	v_mov_b32_e32 v189, v227
	v_mov_b32_e32 v190, v228
	v_mov_b32_e32 v191, v229
	v_mov_b32_dpp v226, v230 row_ror:8 row_mask:0xf bank_mask:0xc
	v_mov_b32_dpp v227, v231 row_ror:8 row_mask:0xf bank_mask:0xc
	v_mov_b32_dpp v228, v232 row_ror:8 row_mask:0xf bank_mask:0xc
	v_mov_b32_dpp v229, v233 row_ror:8 row_mask:0xf bank_mask:0xc
	v_mov_b32_dpp v230, v188 row_ror:8 row_mask:0xf bank_mask:0x3
	v_mov_b32_dpp v231, v189 row_ror:8 row_mask:0xf bank_mask:0x3
	v_mov_b32_dpp v232, v190 row_ror:8 row_mask:0xf bank_mask:0x3
	v_mov_b32_dpp v233, v191 row_ror:8 row_mask:0xf bank_mask:0x3
	v_pk_fma_f32 v[226:227], v[52:53], s[12:13], v[226:227] op_sel_hi:[1,0,1]
	v_pk_fma_f32 v[228:229], v[54:55], s[12:13], v[228:229] op_sel_hi:[1,0,1]
	v_pk_fma_f32 v[230:231], v[48:49], s[12:13], v[230:231] op_sel_hi:[1,0,1]
	v_pk_fma_f32 v[232:233], v[50:51], s[12:13], v[232:233] op_sel_hi:[1,0,1]
	v_cvt_pk_bf16_f32 v48, v226, v227
	v_cvt_pk_bf16_f32 v49, v228, v229
	v_cvt_pk_bf16_f32 v50, v230, v231
	v_cvt_pk_bf16_f32 v51, v232, v233
	v_fmac_f32_e32 v196, v226, v226
	v_fmac_f32_e32 v196, v227, v227
	v_fmac_f32_e32 v196, v228, v228
	v_fmac_f32_e32 v196, v229, v229
	v_fmac_f32_e32 v196, v230, v230
	v_fmac_f32_e32 v196, v231, v231
	v_fmac_f32_e32 v196, v232, v232
	v_fmac_f32_e32 v196, v233, v233
	v_mov_b32_e32 v188, v56
	v_mov_b32_e32 v189, v57
	v_mov_b32_e32 v190, v58
	v_mov_b32_e32 v191, v59
	v_mov_b32_dpp v56, v48 row_ror:8 row_mask:0xf bank_mask:0xc
	v_mov_b32_dpp v57, v49 row_ror:8 row_mask:0xf bank_mask:0xc
	v_mov_b32_dpp v58, v50 row_ror:8 row_mask:0xf bank_mask:0xc
	v_mov_b32_dpp v59, v51 row_ror:8 row_mask:0xf bank_mask:0xc
	v_mov_b32_dpp v48, v188 row_ror:8 row_mask:0xf bank_mask:0x3
	v_mov_b32_dpp v49, v189 row_ror:8 row_mask:0xf bank_mask:0x3
	v_mov_b32_dpp v50, v190 row_ror:8 row_mask:0xf bank_mask:0x3
	v_mov_b32_dpp v51, v191 row_ror:8 row_mask:0xf bank_mask:0x3
	s_mov_b64 s[64:65], 0x84000
	v_lshl_add_u64 v[192:193], v[134:135], 0, s[64:65]
	s_mov_b64 s[66:67], 0x8c400
	v_lshl_add_u64 v[194:195], v[134:135], 0, s[66:67]
	global_store_dwordx4 v[192:193], v[56:59], off
	global_store_dwordx4 v[194:195], v[48:51], off
	v_mov_b32_e32 v197, v196
	s_nop 1
	v_permlane16_swap_b32_e32 v196, v197
	v_add_f32_e32 v196, v196, v197
	v_mov_b32_e32 v197, v196
	s_nop 1
	v_permlane32_swap_b32_e32 v196, v197
	s_and_saveexec_b64 s[22:23], vcc
	v_add_f32_e32 v196, v196, v197
	global_atomic_add_f32 v[198:199], v196, off offset:512
	s_or_b64 exec, exec, s[22:23]
	s_waitcnt vmcnt(8)
; __device__ __forceinline__ float bflo(unsigned w) { return __uint_as_float(w << 16); }
; __device__ __forceinline__ float bfhi(unsigned w) { return __uint_as_float(w & 0xffff0000u); }
; __device__ __forceinline__ u32x4 pack8(f32x4 a, f32x4 b) { u32x4 w; w[0] = cvt_pk_bf16(a[0], a[1]); w[1] = cvt_pk_bf16(a[2], a[3]); w[2] = cvt_pk_bf16(b[0], b[1]); w[3] = cvt_pk_bf16(b[2], b[3]); return w; }
; __device__ __forceinline__ float psum16(float x) { const u32x2s r = __builtin_amdgcn_permlane16_swap(__float_as_uint(x), __float_as_uint(x), false, false); return __uint_as_float(r[0]) + __uint_as_float(r[1]); }
; __device__ __forceinline__ float psum32(float x) { const u32x2s r = __builtin_amdgcn_permlane32_swap(__float_as_uint(x), __float_as_uint(x), false, false); return __uint_as_float(r[0]) + __uint_as_float(r[1]); }
;   __device__ __forceinline__ void operator()(const Acc& acc, const GUnit& u, int wr, int wc, int fr, int fq) const {
;     ...
;         const int row = row0 + ai * 128 + m * 16; const size_t off = (size_t)row * 2048 + col0; float s = 0.f;
; #pragma unroll
;         for (int bj = 0; bj < 2; ++bj) {
;           f32x4 r0, r1;
;           if (R) { r0 = *(const f32x4*)(R + off + bj * 128); r1 = *(const f32x4*)(R + off + bj * 128 + 4); }
;           else { const u32x4 rw = *(const u32x4*)(RB + (size_t)row * ldrb + col0 + bj * 128);
;             r0 = (f32x4){bflo(rw[0]), bfhi(rw[0]), bflo(rw[1]), bfhi(rw[1])}; r1 = (f32x4){bflo(rw[2]), bfhi(rw[2]), bflo(rw[3]), bfhi(rw[3])}; }
;           const f32x4 h0 = r0 + acc[ai][bj][m][0] * osc, h1 = r1 + acc[ai][bj][m][1] * osc;
;           if (H) { *(f32x4*)(H + off + bj * 128) = h0; *(f32x4*)(H + off + bj * 128 + 4) = h1; }
;           if (HB) *(u32x4*)(HB + (size_t)row * ldhb + col0 + bj * 128) = pack8(h0, h1);
;           s += h0[0] * h0[0] + h0[1] * h0[1] + h0[2] * h0[2] + h0[3] * h0[3] + h1[0] * h1[0] + h1[1] * h1[1] + h1[2] * h1[2] + h1[3] * h1[3];
;         }
;         s = psum32(psum16(s));
;         if (fq == 0) atomicAdd(ss + row, s);
	v_mov_b32_e32 v188, v234
	v_mov_b32_e32 v189, v235
	v_mov_b32_e32 v190, v236
	v_mov_b32_e32 v191, v237
	v_mov_b32_dpp v234, v238 row_ror:8 row_mask:0xf bank_mask:0xc
	v_mov_b32_dpp v235, v239 row_ror:8 row_mask:0xf bank_mask:0xc
	v_mov_b32_dpp v236, v240 row_ror:8 row_mask:0xf bank_mask:0xc
	v_mov_b32_dpp v237, v241 row_ror:8 row_mask:0xf bank_mask:0xc
	v_mov_b32_dpp v238, v188 row_ror:8 row_mask:0xf bank_mask:0x3
	v_mov_b32_dpp v239, v189 row_ror:8 row_mask:0xf bank_mask:0x3
	v_mov_b32_dpp v240, v190 row_ror:8 row_mask:0xf bank_mask:0x3
	v_mov_b32_dpp v241, v191 row_ror:8 row_mask:0xf bank_mask:0x3
	v_pk_fma_f32 v[234:235], v[44:45], s[12:13], v[234:235] op_sel_hi:[1,0,1]
	v_pk_fma_f32 v[236:237], v[46:47], s[12:13], v[236:237] op_sel_hi:[1,0,1]
	v_pk_fma_f32 v[238:239], v[40:41], s[12:13], v[238:239] op_sel_hi:[1,0,1]
	v_pk_fma_f32 v[240:241], v[42:43], s[12:13], v[240:241] op_sel_hi:[1,0,1]
	v_cvt_pk_bf16_f32 v40, v234, v235
	v_cvt_pk_bf16_f32 v41, v236, v237
	v_cvt_pk_bf16_f32 v42, v238, v239
	v_cvt_pk_bf16_f32 v43, v240, v241
	v_mul_f32_e32 v196, v234, v234
	v_fmac_f32_e32 v196, v235, v235
	v_fmac_f32_e32 v196, v236, v236
	v_fmac_f32_e32 v196, v237, v237
	v_fmac_f32_e32 v196, v238, v238
	v_fmac_f32_e32 v196, v239, v239
	v_fmac_f32_e32 v196, v240, v240
	v_fmac_f32_e32 v196, v241, v241
	v_mov_b32_e32 v188, v242
	v_mov_b32_e32 v189, v243
	v_mov_b32_e32 v190, v244
	v_mov_b32_e32 v191, v245
	v_mov_b32_dpp v242, v246 row_ror:8 row_mask:0xf bank_mask:0xc
	v_mov_b32_dpp v243, v247 row_ror:8 row_mask:0xf bank_mask:0xc
	v_mov_b32_dpp v244, v248 row_ror:8 row_mask:0xf bank_mask:0xc
	v_mov_b32_dpp v245, v249 row_ror:8 row_mask:0xf bank_mask:0xc
	v_mov_b32_dpp v246, v188 row_ror:8 row_mask:0xf bank_mask:0x3
	v_mov_b32_dpp v247, v189 row_ror:8 row_mask:0xf bank_mask:0x3
	v_mov_b32_dpp v248, v190 row_ror:8 row_mask:0xf bank_mask:0x3
	v_mov_b32_dpp v249, v191 row_ror:8 row_mask:0xf bank_mask:0x3
	v_pk_fma_f32 v[242:243], v[36:37], s[12:13], v[242:243] op_sel_hi:[1,0,1]
	v_pk_fma_f32 v[244:245], v[38:39], s[12:13], v[244:245] op_sel_hi:[1,0,1]
	v_pk_fma_f32 v[246:247], v[32:33], s[12:13], v[246:247] op_sel_hi:[1,0,1]
	v_pk_fma_f32 v[248:249], v[34:35], s[12:13], v[248:249] op_sel_hi:[1,0,1]
	v_cvt_pk_bf16_f32 v32, v242, v243
	v_cvt_pk_bf16_f32 v33, v244, v245
	v_cvt_pk_bf16_f32 v34, v246, v247
	v_cvt_pk_bf16_f32 v35, v248, v249
	v_fmac_f32_e32 v196, v242, v242
	v_fmac_f32_e32 v196, v243, v243
	v_fmac_f32_e32 v196, v244, v244
	v_fmac_f32_e32 v196, v245, v245
	v_fmac_f32_e32 v196, v246, v246
	v_fmac_f32_e32 v196, v247, v247
	v_fmac_f32_e32 v196, v248, v248
	v_fmac_f32_e32 v196, v249, v249
	v_mov_b32_e32 v188, v40
	v_mov_b32_e32 v189, v41
	v_mov_b32_e32 v190, v42
	v_mov_b32_e32 v191, v43
	v_mov_b32_dpp v40, v32 row_ror:8 row_mask:0xf bank_mask:0xc
	v_mov_b32_dpp v41, v33 row_ror:8 row_mask:0xf bank_mask:0xc
	v_mov_b32_dpp v42, v34 row_ror:8 row_mask:0xf bank_mask:0xc
	v_mov_b32_dpp v43, v35 row_ror:8 row_mask:0xf bank_mask:0xc
	v_mov_b32_dpp v32, v188 row_ror:8 row_mask:0xf bank_mask:0x3
	v_mov_b32_dpp v33, v189 row_ror:8 row_mask:0xf bank_mask:0x3
	v_mov_b32_dpp v34, v190 row_ror:8 row_mask:0xf bank_mask:0x3
	v_mov_b32_dpp v35, v191 row_ror:8 row_mask:0xf bank_mask:0x3
	s_mov_b64 s[64:65], 0x94800
	v_lshl_add_u64 v[192:193], v[134:135], 0, s[64:65]
	s_mov_b64 s[66:67], 0x9cc00
	v_lshl_add_u64 v[194:195], v[134:135], 0, s[66:67]
	global_store_dwordx4 v[192:193], v[40:43], off
	global_store_dwordx4 v[194:195], v[32:35], off
	v_mov_b32_e32 v197, v196
	s_nop 1
	v_permlane16_swap_b32_e32 v196, v197
	v_add_f32_e32 v196, v196, v197
	v_mov_b32_e32 v197, v196
	s_nop 1
	v_permlane32_swap_b32_e32 v196, v197
	s_and_saveexec_b64 s[22:23], vcc
	v_add_f32_e32 v196, v196, v197
	global_atomic_add_f32 v[198:199], v196, off offset:576
	s_or_b64 exec, exec, s[22:23]
	s_waitcnt vmcnt(4)
	v_mov_b32_e32 v188, v140
	v_mov_b32_e32 v189, v141
	v_mov_b32_e32 v190, v142
	v_mov_b32_e32 v191, v143
	v_mov_b32_dpp v140, v144 row_ror:8 row_mask:0xf bank_mask:0xc
	v_mov_b32_dpp v141, v145 row_ror:8 row_mask:0xf bank_mask:0xc
	v_mov_b32_dpp v142, v146 row_ror:8 row_mask:0xf bank_mask:0xc
	v_mov_b32_dpp v143, v147 row_ror:8 row_mask:0xf bank_mask:0xc
	v_mov_b32_dpp v144, v188 row_ror:8 row_mask:0xf bank_mask:0x3
	v_mov_b32_dpp v145, v189 row_ror:8 row_mask:0xf bank_mask:0x3
	v_mov_b32_dpp v146, v190 row_ror:8 row_mask:0xf bank_mask:0x3
	v_mov_b32_dpp v147, v191 row_ror:8 row_mask:0xf bank_mask:0x3
	v_pk_fma_f32 v[140:141], v[28:29], s[12:13], v[140:141] op_sel_hi:[1,0,1]
	v_pk_fma_f32 v[142:143], v[30:31], s[12:13], v[142:143] op_sel_hi:[1,0,1]
	v_pk_fma_f32 v[144:145], v[24:25], s[12:13], v[144:145] op_sel_hi:[1,0,1]
	v_pk_fma_f32 v[146:147], v[26:27], s[12:13], v[146:147] op_sel_hi:[1,0,1]
	v_cvt_pk_bf16_f32 v24, v140, v141
	v_cvt_pk_bf16_f32 v25, v142, v143
	v_cvt_pk_bf16_f32 v26, v144, v145
	v_cvt_pk_bf16_f32 v27, v146, v147
	v_mul_f32_e32 v196, v140, v140
	v_fmac_f32_e32 v196, v141, v141
	v_fmac_f32_e32 v196, v142, v142
	v_fmac_f32_e32 v196, v143, v143
	v_fmac_f32_e32 v196, v144, v144
	v_fmac_f32_e32 v196, v145, v145
	v_fmac_f32_e32 v196, v146, v146
	v_fmac_f32_e32 v196, v147, v147
	v_mov_b32_e32 v188, v148
	v_mov_b32_e32 v189, v149
	v_mov_b32_e32 v190, v150
	v_mov_b32_e32 v191, v151
	v_mov_b32_dpp v148, v152 row_ror:8 row_mask:0xf bank_mask:0xc
	v_mov_b32_dpp v149, v153 row_ror:8 row_mask:0xf bank_mask:0xc
	v_mov_b32_dpp v150, v154 row_ror:8 row_mask:0xf bank_mask:0xc
	v_mov_b32_dpp v151, v155 row_ror:8 row_mask:0xf bank_mask:0xc
	v_mov_b32_dpp v152, v188 row_ror:8 row_mask:0xf bank_mask:0x3
	v_mov_b32_dpp v153, v189 row_ror:8 row_mask:0xf bank_mask:0x3
; __device__ __forceinline__ float bflo(unsigned w) { return __uint_as_float(w << 16); }
; __device__ __forceinline__ float bfhi(unsigned w) { return __uint_as_float(w & 0xffff0000u); }
; __device__ __forceinline__ u32x4 pack8(f32x4 a, f32x4 b) { u32x4 w; w[0] = cvt_pk_bf16(a[0], a[1]); w[1] = cvt_pk_bf16(a[2], a[3]); w[2] = cvt_pk_bf16(b[0], b[1]); w[3] = cvt_pk_bf16(b[2], b[3]); return w; }
; __device__ __forceinline__ float psum16(float x) { const u32x2s r = __builtin_amdgcn_permlane16_swap(__float_as_uint(x), __float_as_uint(x), false, false); return __uint_as_float(r[0]) + __uint_as_float(r[1]); }
; __device__ __forceinline__ float psum32(float x) { const u32x2s r = __builtin_amdgcn_permlane32_swap(__float_as_uint(x), __float_as_uint(x), false, false); return __uint_as_float(r[0]) + __uint_as_float(r[1]); }
;   __device__ __forceinline__ void operator()(const Acc& acc, const GUnit& u, int wr, int wc, int fr, int fq) const {
;     ...
;         const int row = row0 + ai * 128 + m * 16; const size_t off = (size_t)row * 2048 + col0; float s = 0.f;
; #pragma unroll
;         for (int bj = 0; bj < 2; ++bj) {
;           f32x4 r0, r1;
;           if (R) { r0 = *(const f32x4*)(R + off + bj * 128); r1 = *(const f32x4*)(R + off + bj * 128 + 4); }
;           else { const u32x4 rw = *(const u32x4*)(RB + (size_t)row * ldrb + col0 + bj * 128);
;             r0 = (f32x4){bflo(rw[0]), bfhi(rw[0]), bflo(rw[1]), bfhi(rw[1])}; r1 = (f32x4){bflo(rw[2]), bfhi(rw[2]), bflo(rw[3]), bfhi(rw[3])}; }
;           const f32x4 h0 = r0 + acc[ai][bj][m][0] * osc, h1 = r1 + acc[ai][bj][m][1] * osc;
;           if (H) { *(f32x4*)(H + off + bj * 128) = h0; *(f32x4*)(H + off + bj * 128 + 4) = h1; }
;           if (HB) *(u32x4*)(HB + (size_t)row * ldhb + col0 + bj * 128) = pack8(h0, h1);
;           s += h0[0] * h0[0] + h0[1] * h0[1] + h0[2] * h0[2] + h0[3] * h0[3] + h1[0] * h1[0] + h1[1] * h1[1] + h1[2] * h1[2] + h1[3] * h1[3];
;         }
;         s = psum32(psum16(s));
;         if (fq == 0) atomicAdd(ss + row, s);
;       }
;   }
	v_mov_b32_dpp v154, v190 row_ror:8 row_mask:0xf bank_mask:0x3
	v_mov_b32_dpp v155, v191 row_ror:8 row_mask:0xf bank_mask:0x3
	v_pk_fma_f32 v[148:149], v[20:21], s[12:13], v[148:149] op_sel_hi:[1,0,1]
	v_pk_fma_f32 v[150:151], v[22:23], s[12:13], v[150:151] op_sel_hi:[1,0,1]
	v_pk_fma_f32 v[152:153], v[16:17], s[12:13], v[152:153] op_sel_hi:[1,0,1]
	v_pk_fma_f32 v[154:155], v[18:19], s[12:13], v[154:155] op_sel_hi:[1,0,1]
	v_cvt_pk_bf16_f32 v16, v148, v149
	v_cvt_pk_bf16_f32 v17, v150, v151
	v_cvt_pk_bf16_f32 v18, v152, v153
	v_cvt_pk_bf16_f32 v19, v154, v155
	v_fmac_f32_e32 v196, v148, v148
	v_fmac_f32_e32 v196, v149, v149
	v_fmac_f32_e32 v196, v150, v150
	v_fmac_f32_e32 v196, v151, v151
	v_fmac_f32_e32 v196, v152, v152
	v_fmac_f32_e32 v196, v153, v153
	v_fmac_f32_e32 v196, v154, v154
	v_fmac_f32_e32 v196, v155, v155
	v_mov_b32_e32 v188, v24
	v_mov_b32_e32 v189, v25
	v_mov_b32_e32 v190, v26
	v_mov_b32_e32 v191, v27
	v_mov_b32_dpp v24, v16 row_ror:8 row_mask:0xf bank_mask:0xc
	v_mov_b32_dpp v25, v17 row_ror:8 row_mask:0xf bank_mask:0xc
	v_mov_b32_dpp v26, v18 row_ror:8 row_mask:0xf bank_mask:0xc
	v_mov_b32_dpp v27, v19 row_ror:8 row_mask:0xf bank_mask:0xc
	v_mov_b32_dpp v16, v188 row_ror:8 row_mask:0xf bank_mask:0x3
	v_mov_b32_dpp v17, v189 row_ror:8 row_mask:0xf bank_mask:0x3
	v_mov_b32_dpp v18, v190 row_ror:8 row_mask:0xf bank_mask:0x3
	v_mov_b32_dpp v19, v191 row_ror:8 row_mask:0xf bank_mask:0x3
	s_mov_b64 s[64:65], 0xa5000
	v_lshl_add_u64 v[192:193], v[134:135], 0, s[64:65]
	s_mov_b64 s[66:67], 0xad400
	v_lshl_add_u64 v[194:195], v[134:135], 0, s[66:67]
	global_store_dwordx4 v[192:193], v[24:27], off
	global_store_dwordx4 v[194:195], v[16:19], off
	v_mov_b32_e32 v197, v196
	s_nop 1
	v_permlane16_swap_b32_e32 v196, v197
	v_add_f32_e32 v196, v196, v197
	v_mov_b32_e32 v197, v196
	s_nop 1
	v_permlane32_swap_b32_e32 v196, v197
	s_and_saveexec_b64 s[22:23], vcc
	v_add_f32_e32 v196, v196, v197
	global_atomic_add_f32 v[198:199], v196, off offset:640
	s_or_b64 exec, exec, s[22:23]
	s_waitcnt vmcnt(0)
	v_mov_b32_e32 v188, v156
	v_mov_b32_e32 v189, v157
	v_mov_b32_e32 v190, v158
	v_mov_b32_e32 v191, v159
	v_mov_b32_dpp v156, v160 row_ror:8 row_mask:0xf bank_mask:0xc
	v_mov_b32_dpp v157, v161 row_ror:8 row_mask:0xf bank_mask:0xc
	v_mov_b32_dpp v158, v162 row_ror:8 row_mask:0xf bank_mask:0xc
	v_mov_b32_dpp v159, v163 row_ror:8 row_mask:0xf bank_mask:0xc
	v_mov_b32_dpp v160, v188 row_ror:8 row_mask:0xf bank_mask:0x3
	v_mov_b32_dpp v161, v189 row_ror:8 row_mask:0xf bank_mask:0x3
	v_mov_b32_dpp v162, v190 row_ror:8 row_mask:0xf bank_mask:0x3
	v_mov_b32_dpp v163, v191 row_ror:8 row_mask:0xf bank_mask:0x3
	v_pk_fma_f32 v[156:157], v[12:13], s[12:13], v[156:157] op_sel_hi:[1,0,1]
	v_pk_fma_f32 v[158:159], v[14:15], s[12:13], v[158:159] op_sel_hi:[1,0,1]
	v_pk_fma_f32 v[160:161], v[8:9], s[12:13], v[160:161] op_sel_hi:[1,0,1]
	v_pk_fma_f32 v[162:163], v[10:11], s[12:13], v[162:163] op_sel_hi:[1,0,1]
	v_cvt_pk_bf16_f32 v8, v156, v157
	v_cvt_pk_bf16_f32 v9, v158, v159
	v_cvt_pk_bf16_f32 v10, v160, v161
	v_cvt_pk_bf16_f32 v11, v162, v163
	v_mul_f32_e32 v196, v156, v156
	v_fmac_f32_e32 v196, v157, v157
	v_fmac_f32_e32 v196, v158, v158
	v_fmac_f32_e32 v196, v159, v159
	v_fmac_f32_e32 v196, v160, v160
	v_fmac_f32_e32 v196, v161, v161
	v_fmac_f32_e32 v196, v162, v162
	v_fmac_f32_e32 v196, v163, v163
	v_mov_b32_e32 v188, v164
	v_mov_b32_e32 v189, v165
	v_mov_b32_e32 v190, v166
	v_mov_b32_e32 v191, v167
	v_mov_b32_dpp v164, v168 row_ror:8 row_mask:0xf bank_mask:0xc
	v_mov_b32_dpp v165, v169 row_ror:8 row_mask:0xf bank_mask:0xc
	v_mov_b32_dpp v166, v170 row_ror:8 row_mask:0xf bank_mask:0xc
	v_mov_b32_dpp v167, v171 row_ror:8 row_mask:0xf bank_mask:0xc
	v_mov_b32_dpp v168, v188 row_ror:8 row_mask:0xf bank_mask:0x3
	v_mov_b32_dpp v169, v189 row_ror:8 row_mask:0xf bank_mask:0x3
	v_mov_b32_dpp v170, v190 row_ror:8 row_mask:0xf bank_mask:0x3
	v_mov_b32_dpp v171, v191 row_ror:8 row_mask:0xf bank_mask:0x3
	v_pk_fma_f32 v[164:165], v[4:5], s[12:13], v[164:165] op_sel_hi:[1,0,1]
	v_pk_fma_f32 v[166:167], v[6:7], s[12:13], v[166:167] op_sel_hi:[1,0,1]
	v_pk_fma_f32 v[168:169], v[0:1], s[12:13], v[168:169] op_sel_hi:[1,0,1]
	v_pk_fma_f32 v[170:171], v[2:3], s[12:13], v[170:171] op_sel_hi:[1,0,1]
	v_cvt_pk_bf16_f32 v0, v164, v165
	v_cvt_pk_bf16_f32 v1, v166, v167
	v_cvt_pk_bf16_f32 v2, v168, v169
	v_cvt_pk_bf16_f32 v3, v170, v171
	v_fmac_f32_e32 v196, v164, v164
	v_fmac_f32_e32 v196, v165, v165
	v_fmac_f32_e32 v196, v166, v166
	v_fmac_f32_e32 v196, v167, v167
	v_fmac_f32_e32 v196, v168, v168
	v_fmac_f32_e32 v196, v169, v169
	v_fmac_f32_e32 v196, v170, v170
	v_fmac_f32_e32 v196, v171, v171
	v_mov_b32_e32 v188, v8
	v_mov_b32_e32 v189, v9
	v_mov_b32_e32 v190, v10
	v_mov_b32_e32 v191, v11
	v_mov_b32_dpp v8, v0 row_ror:8 row_mask:0xf bank_mask:0xc
	v_mov_b32_dpp v9, v1 row_ror:8 row_mask:0xf bank_mask:0xc
	v_mov_b32_dpp v10, v2 row_ror:8 row_mask:0xf bank_mask:0xc
	v_mov_b32_dpp v11, v3 row_ror:8 row_mask:0xf bank_mask:0xc
	v_mov_b32_dpp v0, v188 row_ror:8 row_mask:0xf bank_mask:0x3
	v_mov_b32_dpp v1, v189 row_ror:8 row_mask:0xf bank_mask:0x3
	v_mov_b32_dpp v2, v190 row_ror:8 row_mask:0xf bank_mask:0x3
	v_mov_b32_dpp v3, v191 row_ror:8 row_mask:0xf bank_mask:0x3
	s_mov_b64 s[64:65], 0xb5800
	v_lshl_add_u64 v[192:193], v[134:135], 0, s[64:65]
	s_mov_b64 s[66:67], 0xbdc00
	v_lshl_add_u64 v[194:195], v[134:135], 0, s[66:67]
	global_store_dwordx4 v[192:193], v[8:11], off
	global_store_dwordx4 v[194:195], v[0:3], off
	v_mov_b32_e32 v197, v196
	s_nop 1
	v_permlane16_swap_b32_e32 v196, v197
	v_add_f32_e32 v196, v196, v197
	v_mov_b32_e32 v197, v196
	s_nop 1
	v_permlane32_swap_b32_e32 v196, v197
	s_and_saveexec_b64 s[22:23], vcc
	v_add_f32_e32 v196, v196, v197
	global_atomic_add_f32 v[198:199], v196, off offset:704
	s_or_b64 exec, exec, s[22:23]
	v_readlane_b32 s48, v254, 0
	v_readlane_b32 s49, v254, 1
	v_readlane_b32 s50, v254, 2
	v_readlane_b32 s51, v254, 3
	v_readlane_b32 s52, v254, 4
	v_readlane_b32 s53, v254, 5
	v_readlane_b32 s54, v254, 6
	v_readlane_b32 s55, v254, 7
	v_readlane_b32 s56, v254, 8
	v_readlane_b32 s57, v254, 9
	v_readlane_b32 s58, v254, 10
	v_readlane_b32 s59, v254, 11
	v_readlane_b32 s60, v254, 12
	v_readlane_b32 s61, v254, 13
	v_readlane_b32 s62, v254, 14
	v_readlane_b32 s63, v254, 15
	s_andn2_b64 vcc, exec, s[14:15]
	s_mov_b64 s[14:15], -1
	s_cbranch_vccnz .LBB0_1070
	s_andn2_b64 vcc, exec, s[4:5]
	s_cbranch_vccnz .LBB0_1069
	s_barrier
	s_branch .LBB0_1069

; __device__ __forceinline__ float bflo(unsigned w) { return __uint_as_float(w << 16); }
; __device__ __forceinline__ float bfhi(unsigned w) { return __uint_as_float(w & 0xffff0000u); }
; __device__ __forceinline__ void p10_final(const Params& p, int bid, int nb) {
;   int tid = threadIdx.x; asm volatile("" : "+v"(tid));
;   const int lane = tid & 63, wid = tid >> 6;
;   const float* ss2 = (const float*)(p.ws + OFF_SS) + 2 * T;
;   const bf16_t* h2 = (const bf16_t*)(p.ws + OFF_RQ);
;   f32x4 g[8];
; #pragma unroll
;   for (int j = 0; j < 8; ++j) g[j] = *(const f32x4*)((const float*)(p.ws + OFF_SMALL) + SM_FINAL + (lane + 64 * j) * 4);
;   for (int row = bid * 8 + wid; row < T; row += nb * 8) {
;     const float r = rsqrtf(ss2[row] * (1.f / 2048.f) + EPS);
;     f32x4* ptr = (f32x4*)(p.out + (size_t)row * D);
;     u32x2 hv[8];
; #pragma unroll
;     for (int j = 0; j < 8; ++j) hv[j] = *(const u32x2*)(h2 + (size_t)row * D + (lane + 64 * j) * 4);
; #pragma unroll
;     for (int j = 0; j < 8; ++j) { const f32x4 v = {bflo(hv[j][0]), bfhi(hv[j][0]), bflo(hv[j][1]), bfhi(hv[j][1])}; ptr[lane + 64 * j] = v * r * g[j]; }
;   }
; }
.LBB0_1245:
	s_or_b64 exec, exec, s[2:3]
	s_barrier
	v_readlane_b32 s2, v254, 22
	v_ashrrev_i32_e32 v0, 6, v200
	s_mov_b32 s1, 0x8000
	v_add_u32_e32 v32, s2, v0
	v_cmp_gt_i32_e32 vcc, s1, v32
	v_readlane_b32 s3, v254, 23
	s_and_saveexec_b64 s[2:3], vcc
	v_readlane_b32 s12, v254, 16
	v_readlane_b32 s13, v254, 17
	v_readlane_b32 s14, v254, 18
	v_readlane_b32 s15, v254, 19
	s_cbranch_execz .LBB0_1248
	v_and_b32_e32 v40, 63, v200
	s_add_u32 s2, s14, 0x3eb69600
	v_lshlrev_b32_e32 v38, 4, v40
	s_addc_u32 s3, s15, 0
	v_or_b32_e32 v8, 0x400, v38
	v_or_b32_e32 v16, 0x800, v38
	v_or_b32_e32 v17, 0xc00, v38
	v_or_b32_e32 v24, 0x1000, v38
	v_or_b32_e32 v25, 0x1400, v38
	v_or_b32_e32 v33, 0x1800, v38
	global_load_dwordx4 v[0:3], v38, s[2:3]
	global_load_dwordx4 v[4:7], v8, s[2:3]
	s_nop 0
	global_load_dwordx4 v[8:11], v16, s[2:3]
	global_load_dwordx4 v[12:15], v17, s[2:3]
	s_nop 0
	global_load_dwordx4 v[16:19], v24, s[2:3]
	global_load_dwordx4 v[20:23], v25, s[2:3]
	v_or_b32_e32 v34, 0x1c00, v38
	global_load_dwordx4 v[24:27], v33, s[2:3]
	global_load_dwordx4 v[28:31], v34, s[2:3]
	v_ashrrev_i32_e32 v33, 31, v32
	v_lshlrev_b64 v[36:37], 13, v[32:33]
	v_or_b32_e32 v36, v36, v38
	v_mov_b64_e32 v[34:35], 0x3eb40000
	s_ashr_i32 s1, s0, 31
	v_lshl_add_u64 v[36:37], s[12:13], 0, v[36:37]
	s_mov_b64 s[4:5], 0x1000
	v_lshlrev_b64 v[38:39], 12, v[32:33]
	v_lshl_add_u64 v[34:35], v[32:33], 2, v[34:35]
	s_lshl_b64 s[2:3], s[0:1], 2
	v_lshl_add_u64 v[36:37], v[36:37], 0, s[4:5]
	s_lshl_b64 s[4:5], s[0:1], 13
	v_lshl_or_b32 v38, v40, 3, v38
	s_lshl_b64 s[6:7], s[0:1], 12
	s_mov_b64 s[8:9], 0
	v_mov_b32_e32 v33, 0x358637bd
	s_mov_b32 s1, 0x800000
	s_movk_i32 s10, 0x7fff
	v_lshl_add_u64 v[102:103], s[14:15], 0, v[34:35]
	v_lshl_add_u64 v[104:105], s[14:15], 0, v[38:39]
	global_load_dword v100, v[102:103], off
	global_load_dwordx2 v[84:85], v[104:105], off
	global_load_dwordx2 v[86:87], v[104:105], off offset:512
	global_load_dwordx2 v[88:89], v[104:105], off offset:1024
	global_load_dwordx2 v[90:91], v[104:105], off offset:1536
	global_load_dwordx2 v[92:93], v[104:105], off offset:2048
	global_load_dwordx2 v[94:95], v[104:105], off offset:2560
	global_load_dwordx2 v[96:97], v[104:105], off offset:3072
	global_load_dwordx2 v[98:99], v[104:105], off offset:3584
	s_waitcnt vmcnt(0)
	s_branch .Lp10_body
.Lp10_loop:
	s_waitcnt vmcnt(8)
.Lp10_body:
	v_fmamk_f32 v72, v100, 0x3a000000, v33
	v_mul_f32_e32 v73, 0x4b800000, v72
	v_cmp_gt_f32_e32 vcc, s1, v72
	v_lshlrev_b32_e32 v40, 16, v84
	v_and_b32_e32 v41, 0xffff0000, v84
	v_cndmask_b32_e32 v72, v72, v73, vcc
	v_rsq_f32_e32 v72, v72
	v_lshlrev_b32_e32 v42, 16, v85
	v_and_b32_e32 v43, 0xffff0000, v85
	v_lshlrev_b32_e32 v44, 16, v86
	v_mul_f32_e32 v73, 0x45800000, v72
	v_cndmask_b32_e32 v72, v72, v73, vcc
	v_and_b32_e32 v45, 0xffff0000, v86
	v_lshlrev_b32_e32 v46, 16, v87
	v_and_b32_e32 v47, 0xffff0000, v87
	v_lshlrev_b32_e32 v60, 16, v88
	v_and_b32_e32 v61, 0xffff0000, v88
	v_lshlrev_b32_e32 v48, 16, v89
	v_and_b32_e32 v49, 0xffff0000, v89
	v_lshlrev_b32_e32 v62, 16, v90
	v_and_b32_e32 v63, 0xffff0000, v90
	v_lshlrev_b32_e32 v50, 16, v91
	v_and_b32_e32 v51, 0xffff0000, v91
	v_lshlrev_b32_e32 v64, 16, v92
	v_and_b32_e32 v65, 0xffff0000, v92
	v_lshlrev_b32_e32 v52, 16, v93
	v_and_b32_e32 v53, 0xffff0000, v93
	v_lshlrev_b32_e32 v66, 16, v94
	v_and_b32_e32 v67, 0xffff0000, v94
	v_lshlrev_b32_e32 v54, 16, v95
	v_and_b32_e32 v55, 0xffff0000, v95
	v_lshlrev_b32_e32 v68, 16, v96
	v_and_b32_e32 v69, 0xffff0000, v96
	v_lshlrev_b32_e32 v56, 16, v97
	v_and_b32_e32 v57, 0xffff0000, v97
	v_lshlrev_b32_e32 v70, 16, v98
	v_and_b32_e32 v71, 0xffff0000, v98
	v_lshlrev_b32_e32 v58, 16, v99
	v_and_b32_e32 v59, 0xffff0000, v99
	v_add_u32_e32 v32, s0, v32
	v_cmp_lt_i32_e32 vcc, s10, v32
	s_or_b64 s[8:9], vcc, s[8:9]
	s_and_b64 vcc, exec, s[8:9]
	s_cbranch_vccnz .Lp10_noadv
	v_lshl_add_u64 v[34:35], v[34:35], 0, s[2:3]
	v_lshl_add_u64 v[38:39], v[38:39], 0, s[6:7]
.Lp10_noadv:
	v_lshl_add_u64 v[102:103], s[14:15], 0, v[34:35]
	v_lshl_add_u64 v[104:105], s[14:15], 0, v[38:39]
	global_load_dword v100, v[102:103], off
	global_load_dwordx2 v[84:85], v[104:105], off
	global_load_dwordx2 v[86:87], v[104:105], off offset:512
	global_load_dwordx2 v[88:89], v[104:105], off offset:1024
	global_load_dwordx2 v[90:91], v[104:105], off offset:1536
	global_load_dwordx2 v[92:93], v[104:105], off offset:2048
	global_load_dwordx2 v[94:95], v[104:105], off offset:2560
	global_load_dwordx2 v[96:97], v[104:105], off offset:3072
	global_load_dwordx2 v[98:99], v[104:105], off offset:3584
	v_pk_mul_f32 v[40:41], v[72:73], v[40:41] op_sel_hi:[0,1]
	v_pk_mul_f32 v[42:43], v[72:73], v[42:43] op_sel_hi:[0,1]
	v_pk_mul_f32 v[44:45], v[72:73], v[44:45] op_sel_hi:[0,1]
	v_pk_mul_f32 v[46:47], v[72:73], v[46:47] op_sel_hi:[0,1]
	v_pk_mul_f32 v[60:61], v[72:73], v[60:61] op_sel_hi:[0,1]
	v_pk_mul_f32 v[48:49], v[72:73], v[48:49] op_sel_hi:[0,1]
	v_pk_mul_f32 v[62:63], v[72:73], v[62:63] op_sel_hi:[0,1]
	v_pk_mul_f32 v[74:75], v[72:73], v[50:51] op_sel_hi:[0,1]
	v_pk_mul_f32 v[64:65], v[72:73], v[64:65] op_sel_hi:[0,1]
	v_pk_mul_f32 v[76:77], v[72:73], v[52:53] op_sel_hi:[0,1]
	v_pk_mul_f32 v[66:67], v[72:73], v[66:67] op_sel_hi:[0,1]
	v_pk_mul_f32 v[78:79], v[72:73], v[54:55] op_sel_hi:[0,1]
	v_pk_mul_f32 v[68:69], v[72:73], v[68:69] op_sel_hi:[0,1]
	v_pk_mul_f32 v[80:81], v[72:73], v[56:57] op_sel_hi:[0,1]
	v_pk_mul_f32 v[82:83], v[72:73], v[70:71] op_sel_hi:[0,1]
	v_pk_mul_f32 v[70:71], v[72:73], v[58:59] op_sel_hi:[0,1]
	v_pk_mul_f32 v[42:43], v[2:3], v[42:43]
	v_pk_mul_f32 v[40:41], v[0:1], v[40:41]
	v_pk_mul_f32 v[46:47], v[6:7], v[46:47]
	v_pk_mul_f32 v[44:45], v[4:5], v[44:45]
	v_pk_mul_f32 v[50:51], v[10:11], v[48:49]
	v_pk_mul_f32 v[48:49], v[8:9], v[60:61]
	v_pk_mul_f32 v[54:55], v[14:15], v[74:75]
	v_pk_mul_f32 v[52:53], v[12:13], v[62:63]
	v_pk_mul_f32 v[58:59], v[18:19], v[76:77]
	v_pk_mul_f32 v[56:57], v[16:17], v[64:65]
	v_pk_mul_f32 v[62:63], v[22:23], v[78:79]
	v_pk_mul_f32 v[60:61], v[20:21], v[66:67]
	v_pk_mul_f32 v[66:67], v[26:27], v[80:81]
	v_pk_mul_f32 v[64:65], v[24:25], v[68:69]
	v_pk_mul_f32 v[70:71], v[30:31], v[70:71]
	v_pk_mul_f32 v[68:69], v[28:29], v[82:83]
	global_store_dwordx4 v[36:37], v[40:43], off offset:-4096
	global_store_dwordx4 v[36:37], v[44:47], off offset:-3072
	global_store_dwordx4 v[36:37], v[48:51], off offset:-2048
	global_store_dwordx4 v[36:37], v[52:55], off offset:-1024
	global_store_dwordx4 v[36:37], v[56:59], off
	global_store_dwordx4 v[36:37], v[60:63], off offset:1024
	global_store_dwordx4 v[36:37], v[64:67], off offset:2048
	global_store_dwordx4 v[36:37], v[68:71], off offset:3072
	v_lshl_add_u64 v[36:37], v[36:37], 0, s[4:5]
	s_andn2_b64 exec, exec, s[8:9]
	s_cbranch_execnz .Lp10_loop
